# attention tile loop sw-pipelined + scalar checks + subln load hoist; XCD-local barriers (with runtime placement check + global fallback) at G1->M1 and M1->M2 seams
# speedup vs baseline: 1.0406x; 1.0164x over previous
.LBB0_3:
	s_or_b64 exec, exec, s[0:1]
	v_readlane_b32 s0, v252, 0
	v_readlane_b32 s1, v252, 1
	s_waitcnt lgkmcnt(0)
	s_barrier
	s_load_dwordx4 s[4:7], s[0:1], 0xd8
	s_getreg_b32 s3, hwreg(HW_REG_XCC_ID, 0, 4)
	s_waitcnt lgkmcnt(0)
	s_add_u32 s0, s4, 0x4000
	v_writelane_b32 v252, s4, 7
	s_addc_u32 s1, s5, 0
	s_and_b32 s33, s3, 15
	v_writelane_b32 v252, s5, 8
	v_writelane_b32 v252, s6, 9
	v_writelane_b32 v252, s7, 10
	v_cmp_eq_u32_e64 s[2:3], 0, v0
	s_nop 1
	v_writelane_b32 v252, s2, 11
	s_nop 1
	v_writelane_b32 v252, s3, 12
	s_and_saveexec_b64 s[4:5], s[2:3]
	s_cbranch_execz .LBB0_6
	s_mov_b64 s[6:7], exec
	v_mbcnt_lo_u32_b32 v1, s6, 0
	v_mbcnt_hi_u32_b32 v1, s7, v1
	v_cmp_eq_u32_e32 vcc, 0, v1
	s_and_b64 s[8:9], exec, vcc
	s_mov_b64 exec, s[8:9]
	s_cbranch_execz .LBB0_6
	s_lshl_b32 s3, s33, 8
	s_bcnt1_i32_b64 s6, s[6:7]
	v_mov_b32_e32 v1, s3
	v_mov_b32_e32 v2, s6
	global_atomic_add v1, v2, s[0:1] offset:1024
	v_readlane_b32 s6, v252, 5
	s_nop 3
	s_and_b32 s6, s6, 7
	s_add_i32 s7, s6, 1
	s_sub_i32 s6, 8, s6
	v_add_u32_e32 v1, 0x4800, v1
	v_mov_b32_e32 v2, s7
	global_atomic_umax v1, v2, s[0:1]
	v_add_u32_e32 v1, 0x1000, v1
	v_mov_b32_e32 v2, s6
	global_atomic_umax v1, v2, s[0:1]

.LBB0_77:
	v_readlane_b32 s74, v252, 7
	v_readlane_b32 s75, v252, 8
	s_nop 3
	s_add_u32 s74, s74, 0x4000
	s_addc_u32 s75, s75, 0
	v_and_b32_e32 v20, 15, v0
	v_lshlrev_b32_e32 v20, 8, v20
	v_add_u32_e32 v22, 0x4800, v20
	v_add_u32_e32 v25, 0x5800, v20
	global_load_dword v21, v20, s[74:75] offset:1024 sc1
	global_load_dword v23, v22, s[74:75] sc1
	global_load_dword v24, v25, s[74:75] sc1
	s_waitcnt vmcnt(0)
	v_add_u32_e32 v23, v23, v24
	v_cmp_ne_u32_e64 s[76:77], 0, v21
	v_cmp_ne_u32_e64 s[78:79], 32, v21
	v_cmp_ne_u32_e64 s[80:81], 9, v23
	s_nop 3
	s_or_b64 s[78:79], s[78:79], s[80:81]
	s_and_b64 s[76:77], s[76:77], s[78:79]
	s_cmp_eq_u64 s[76:77], 0
	s_cselect_b32 s74, 1, 0
	v_writelane_b32 v255, s74, 62
	v_readlane_b32 s11, v252, 5
	s_cmpk_lt_i32 s11, 0x240
	s_cselect_b64 s[6:7], -1, 0
	v_writelane_b32 v252, s6, 13
	s_ashr_i32 s2, s11, 31
	s_mov_b32 s35, 0
	v_writelane_b32 v252, s7, 14
	v_writelane_b32 v252, s2, 15
	s_lshr_b32 s6, s2, 29
	v_readlane_b32 s19, v252, 4
	s_add_i32 s6, s11, s6
	s_lshr_b32 s7, s19, 31
	s_ashr_i32 s8, s6, 3
	s_and_b32 s6, s6, -8
	s_add_i32 s7, s19, s7
	s_sub_i32 s9, s11, s6
	s_ashr_i32 s2, s19, 31
	s_add_i32 s6, s11, 0xc0
	s_ashr_i32 s10, s7, 1
	s_cmp_ge_i32 s11, s10
	s_cselect_b64 s[12:13], -1, 0
	s_sub_i32 s7, s19, s10
	s_sub_i32 s10, s11, s10
	v_writelane_b32 v252, s2, 16
	s_lshl_b32 s10, s10, 3
	v_writelane_b32 v252, s12, 17
	s_add_i32 s16, s10, s3
	s_lshl_b32 s2, s7, 3
	v_writelane_b32 v252, s13, 18
	s_cmpk_lt_u32 s16, 0xd00
	v_writelane_b32 v252, s2, 19
	s_cselect_b64 s[12:13], -1, 0
	v_writelane_b32 v252, s12, 20
	s_add_i32 s2, s16, 0x500
	s_lshl_b32 s10, s3, 14
	v_writelane_b32 v252, s13, 21
	v_writelane_b32 v252, s2, 22
	s_add_i32 s2, s10, 0
	v_writelane_b32 v252, s2, 23
	v_mov_b32_e32 v3, 0
	v_readlane_b32 s12, v252, 7
	v_readlane_b32 s13, v252, 8
	s_add_u32 s20, s12, 0x4200
	s_addc_u32 s21, s13, 0
	v_readlane_b32 s14, v252, 9
	v_readlane_b32 s15, v252, 10
	v_writelane_b32 v252, s20, 24
	v_mov_b32_e32 v215, 0x358637bd
	v_mov_b32_e32 v216, 0x260
	v_writelane_b32 v252, s21, 25
	s_add_u32 s20, s12, 0x4400
	s_addc_u32 s21, s13, 0
	v_writelane_b32 v252, s20, 26
	v_mov_b32_e32 v217, 1
	v_mov_b32_e32 v219, 0xffffca00
	v_writelane_b32 v252, s21, 27
	s_add_u32 s20, s12, 0x4500
	s_addc_u32 s21, s13, 0
	v_writelane_b32 v252, s20, 28
	v_mov_b32_e32 v220, 0xffffdc00
	v_mov_b32_e32 v221, 0xffffee00
	v_writelane_b32 v252, s21, 29
	s_add_u32 s20, s12, 0x4600
	s_addc_u32 s21, s13, 0
	v_writelane_b32 v252, s20, 30
	v_mov_b32_e32 v222, 0x1200
	v_mov_b32_e32 v223, 0x2400
	v_writelane_b32 v252, s21, 31
	s_add_u32 s20, s12, 0x4700
	s_addc_u32 s21, s13, 0
	v_writelane_b32 v252, s20, 32
	v_mov_b32_e32 v224, 0x3600
	v_mov_b32_e32 v226, 0xffffb800
	v_writelane_b32 v252, s21, 33
	s_add_u32 s20, s12, 0x4800
	s_addc_u32 s21, s13, 0
	v_writelane_b32 v252, s20, 34
	v_mov_b32_e32 v227, 0xffffa600
	v_mov_b32_e32 v228, 0xffff9400
	v_writelane_b32 v252, s21, 35
	s_add_u32 s20, s12, 0x4900
	s_addc_u32 s21, s13, 0
	v_writelane_b32 v252, s20, 36
	v_mov_b32_e32 v229, 0xffff8200
	v_mov_b32_e32 v231, 0x90000
	v_writelane_b32 v252, s21, 37
	s_add_u32 s20, s12, 0x4a00
	s_addc_u32 s21, s13, 0
	v_writelane_b32 v252, s20, 38
	v_mov_b32_e32 v232, 0xff800000
	v_mov_b64_e32 v[168:169], 0x100
	v_writelane_b32 v252, s21, 39
	s_add_u32 s20, s12, 0x4b00
	s_addc_u32 s21, s13, 0
	v_writelane_b32 v252, s20, 40
	v_mov_b64_e32 v[170:171], 0xff
	v_mov_b64_e32 v[172:173], 0x580
	v_writelane_b32 v252, s21, 41
	s_add_u32 s20, s12, 0x4c00
	s_addc_u32 s21, s13, 0
	v_writelane_b32 v252, s20, 42
	v_mov_b64_e32 v[174:175], 0x57f
	s_movk_i32 s36, 0x4000
	v_writelane_b32 v252, s21, 43
	s_add_u32 s20, s12, 0x4d00
	s_addc_u32 s21, s13, 0
	v_writelane_b32 v252, s20, 44
	s_movk_i32 s37, 0x6000
	s_mov_b32 s26, s35
	v_writelane_b32 v252, s21, 45
	s_add_u32 s20, s12, 0x4e00
	s_addc_u32 s21, s13, 0
	v_writelane_b32 v252, s20, 46
	s_nop 1
	v_writelane_b32 v252, s21, 47
	s_add_u32 s20, s12, 0x4f00
	s_addc_u32 s21, s13, 0
	v_writelane_b32 v252, s20, 48
	s_nop 1
	v_writelane_b32 v252, s21, 49
	s_add_u32 s20, s12, 0x5000
	s_addc_u32 s21, s13, 0
	v_writelane_b32 v252, s20, 50
	s_nop 1
	v_writelane_b32 v252, s21, 51
	s_add_u32 s20, s12, 0x5100
	s_addc_u32 s21, s13, 0
	v_writelane_b32 v252, s20, 52
	s_nop 1
	v_writelane_b32 v252, s21, 53
	s_add_u32 s20, s12, 0x5200
	s_addc_u32 s21, s13, 0
	v_writelane_b32 v252, s20, 54
	s_nop 1
	v_writelane_b32 v252, s21, 55
	s_add_u32 s20, s12, 0x5300
	s_addc_u32 s21, s13, 0
	v_writelane_b32 v252, s20, 56
	s_cmp_eq_u32 s33, 15
	s_nop 0
	v_writelane_b32 v252, s21, 57
	s_cselect_b64 s[20:21], -1, 0
	v_writelane_b32 v252, s20, 58
	s_cmp_eq_u32 s33, 14
	s_nop 0
	v_writelane_b32 v252, s21, 59
	s_cselect_b64 s[20:21], -1, 0
	v_writelane_b32 v252, s20, 60
	s_cmp_eq_u32 s33, 13
	s_nop 0
	v_writelane_b32 v252, s21, 61
	s_cselect_b64 s[20:21], -1, 0
	v_writelane_b32 v252, s20, 62
	s_cmp_eq_u32 s33, 12
	s_nop 0
	v_writelane_b32 v252, s21, 63
	s_cselect_b64 s[20:21], -1, 0
	v_writelane_b32 v253, s20, 0
	s_cmp_eq_u32 s33, 11
	s_nop 0
	v_writelane_b32 v253, s21, 1
	s_cselect_b64 s[20:21], -1, 0
	v_writelane_b32 v253, s20, 2
	s_cmp_eq_u32 s33, 10
	s_nop 0
	v_writelane_b32 v253, s21, 3
	s_cselect_b64 s[20:21], -1, 0
	v_writelane_b32 v253, s20, 4
	s_cmp_eq_u32 s33, 9
	s_nop 0
	v_writelane_b32 v253, s21, 5
	s_cselect_b64 s[20:21], -1, 0
	v_writelane_b32 v253, s20, 6
	s_cmp_eq_u32 s33, 8
	s_nop 0
	v_writelane_b32 v253, s21, 7
	s_cselect_b64 s[20:21], -1, 0
	v_writelane_b32 v253, s20, 8
	s_cmp_eq_u32 s33, 7
	s_nop 0
	v_writelane_b32 v253, s21, 9
	s_cselect_b64 s[20:21], -1, 0
	v_writelane_b32 v253, s20, 10
	s_cmp_eq_u32 s33, 6
	s_nop 0
	v_writelane_b32 v253, s21, 11
	s_cselect_b64 s[20:21], -1, 0
	v_writelane_b32 v253, s20, 12
	s_cmp_eq_u32 s33, 5
	s_nop 0
	v_writelane_b32 v253, s21, 13
	s_cselect_b64 s[20:21], -1, 0
	v_writelane_b32 v253, s20, 14
	s_cmp_eq_u32 s33, 4
	s_nop 0
	v_writelane_b32 v253, s21, 15
	s_cselect_b64 s[20:21], -1, 0
	v_writelane_b32 v253, s20, 16
	s_cmp_eq_u32 s33, 3
	s_nop 0
	v_writelane_b32 v253, s21, 17
	s_cselect_b64 s[20:21], -1, 0
	v_writelane_b32 v253, s20, 18
	s_cmp_eq_u32 s33, 2
	s_nop 0
	v_writelane_b32 v253, s21, 19
	s_cselect_b64 s[20:21], -1, 0
	v_writelane_b32 v253, s20, 20
	s_cmp_eq_u32 s33, 1
	s_nop 0
	v_writelane_b32 v253, s21, 21
	s_cselect_b64 s[20:21], -1, 0
	v_writelane_b32 v253, s20, 22
	s_cmp_eq_u32 s33, 0
	s_mov_b32 s33, 0xffff0000
	v_writelane_b32 v253, s21, 23
	s_cselect_b64 s[20:21], -1, 0
	s_lshl_b64 s[4:5], s[4:5], 2
	s_add_u32 s0, s0, s4
	s_addc_u32 s1, s1, s5
	v_writelane_b32 v253, s20, 24
	s_add_u32 s4, s0, 0x1400
	s_addc_u32 s5, s1, 0
	v_writelane_b32 v253, s21, 25
	v_writelane_b32 v253, s4, 26
	v_readlane_b32 s20, v252, 6
	s_nop 0
	v_writelane_b32 v253, s5, 27
	s_add_u32 s4, s12, 0x7500
	s_addc_u32 s5, s13, 0
	v_writelane_b32 v253, s4, 28
	s_nop 1
	v_writelane_b32 v253, s5, 29
	s_add_u32 s4, s12, 0x7400
	s_addc_u32 s5, s13, 0
	v_writelane_b32 v253, s4, 30
	s_add_u32 s0, s0, 0x2400
	s_addc_u32 s1, s1, 0
	v_writelane_b32 v253, s5, 31
	v_writelane_b32 v253, s0, 32
	s_cmpk_lt_i32 s20, 0x100
	s_nop 0
	v_writelane_b32 v253, s1, 33
	s_cselect_b64 s[0:1], -1, 0
	v_writelane_b32 v253, s0, 34
	s_lshr_b32 s10, s54, 8
	s_nop 0
	v_writelane_b32 v253, s1, 35
	s_lshl_b32 s0, s3, 4
	s_and_b32 s2, s0, 0x3fffffe0
	s_and_b32 s0, s0, 32
	v_writelane_b32 v253, s0, 36
	s_and_b32 s0, s54, 64
	v_writelane_b32 v253, s0, 37
	s_or_b32 s0, s0, 32
	s_cmpk_lt_i32 s20, 0x200
	v_writelane_b32 v253, s0, 38
	s_cselect_b64 s[0:1], -1, 0
	v_writelane_b32 v253, s0, 39
	s_nop 1
	v_writelane_b32 v253, s1, 40
	s_lshr_b32 s0, s54, 7
	s_mul_i32 s1, s0, 0x2200
	s_add_i32 s21, s1, 0
	s_lshl_b32 s1, s3, 5
	s_and_b32 s5, s1, 32
	s_mul_i32 s1, s2, 0x90
	v_writelane_b32 v253, s2, 41
	s_add_i32 s2, s1, 0
	s_mul_i32 s1, s5, 0x110
	v_writelane_b32 v253, s1, 42
	s_add_i32 s1, s1, 0
	s_lshl_b32 s4, s5, 7
	s_sub_i32 s4, s1, s4
	v_writelane_b32 v253, s4, 43
	s_mul_i32 s4, s5, 0x90
	s_add_i32 s4, s4, 0
	v_writelane_b32 v253, s5, 44
	s_add_i32 s4, s4, 0x15600
	v_writelane_b32 v253, s4, 45
	s_add_i32 s4, s1, 0x15400
	v_writelane_b32 v253, s4, 46
	s_lshl_b32 s4, s19, 1
	s_lshl_b32 s12, s0, 5
	v_writelane_b32 v253, s4, 47
	s_bfe_u32 s4, s54, 0x10006
	s_add_i32 s13, s12, 32
	v_writelane_b32 v253, s2, 48
	s_add_i32 s2, s2, 0x10e00
	s_lshl_b32 s5, s4, 1
	s_cmp_le_u32 s5, s0
	v_writelane_b32 v253, s2, 49
	s_cselect_b64 s[22:23], -1, 0
	v_writelane_b32 v253, s22, 50
	s_cmp_lt_u32 s5, s0
	s_nop 0
	v_writelane_b32 v253, s23, 51
	s_cselect_b64 s[22:23], -1, 0
	v_writelane_b32 v253, s22, 52
	s_lshl_b32 s0, s4, 7
	s_add_i32 s0, s0, 0
	v_writelane_b32 v253, s23, 53
	v_writelane_b32 v253, s0, 54
	s_lshl_b32 s0, s4, 6
	v_writelane_b32 v253, s0, 55
	s_or_b32 s2, s12, 8
	v_writelane_b32 v253, s2, 56
	s_or_b32 s2, s12, 16
	v_writelane_b32 v253, s2, 57
	v_writelane_b32 v253, s12, 58
	s_or_b32 s2, s12, 24
	s_lshl_b32 s0, s4, 5
	v_writelane_b32 v253, s2, 59
	v_writelane_b32 v253, s0, 60
	s_or_b32 s0, s0, 64
	v_writelane_b32 v253, s0, 61
	s_bfe_u32 s22, s54, 0x20006
	s_lshl_b32 s0, s10, 5
	s_lshl_b32 s5, s10, 6
	s_cmpk_lt_u32 s54, 0x100
	s_cselect_b64 s[38:39], -1, 0
	s_cmpk_gt_u32 s54, 0xff
	s_cselect_b64 s[24:25], -1, 0
	s_lshl_b32 s2, s3, 13
	v_writelane_b32 v253, s10, 62
	s_add_i32 s3, s2, 0
	s_xor_b32 s2, s2, 0x8000
	v_writelane_b32 v253, s24, 63
	s_add_i32 s2, s2, 0
	s_cmpk_lt_i32 s11, 0x100
	v_writelane_b32 v254, s25, 0
	v_writelane_b32 v254, s3, 1
	v_writelane_b32 v254, s2, 2
	s_cselect_b64 s[2:3], -1, 0
	v_writelane_b32 v254, s2, 3
	s_nop 1
	v_writelane_b32 v254, s3, 4
	s_lshl_b32 s2, s9, 5
	s_cmpk_lt_i32 s11, 0x580
	s_cselect_b64 s[10:11], -1, 0
	v_writelane_b32 v254, s10, 5
	s_cmpk_lt_u32 s16, 0x580
	s_mul_i32 s3, s9, 33
	v_writelane_b32 v254, s11, 6
	s_cselect_b64 s[10:11], -1, 0
	v_writelane_b32 v254, s10, 7
	s_add_i32 s23, s16, 0x1200
	s_cmpk_lt_i32 s16, 0x500
	v_writelane_b32 v254, s11, 8
	v_writelane_b32 v254, s16, 9
	s_cselect_b64 s[10:11], -1, 0
	v_writelane_b32 v254, s10, 10
	s_cmp_gt_i32 s15, 7
	s_nop 0
	v_writelane_b32 v254, s11, 11
	s_cselect_b64 s[10:11], -1, 0
	s_cmp_lt_i32 s9, 0
	s_cselect_b32 s2, s3, s2
	s_movk_i32 s3, 0x49
	v_writelane_b32 v254, s10, 12
	s_cselect_b32 s3, s3, 0x48
	s_mul_i32 s3, s9, s3
	v_writelane_b32 v254, s11, 13
	s_movk_i32 s10, 0xb1
	s_cselect_b32 s10, s10, 0xb0
	s_add_i32 s3, s3, s8
	s_mul_hi_i32 s11, s3, 0x38e38e39
	s_lshr_b32 s12, s11, 31
	s_ashr_i32 s11, s11, 4
	s_add_i32 s11, s11, s12
	s_mul_i32 s12, s11, 0x48
	s_sub_i32 s3, s3, s12
	s_bfe_i32 s12, s3, 0x80000
	s_bfe_u32 s12, s12, 0x3000c
	s_add_i32 s12, s3, s12
	s_and_b32 s14, s12, 0xf8
	s_add_i32 s2, s2, s8
	s_sub_i32 s3, s3, s14
	s_ashr_i32 s14, s2, 31
	s_mul_i32 s9, s9, s10
	s_lshr_b32 s14, s14, 27
	s_add_i32 s9, s9, s8
	s_add_i32 s14, s2, s14
	s_mul_hi_i32 s8, s9, 0x2e8ba2e9
	s_and_b32 s15, s14, 0xffe0
	s_lshr_b32 s10, s8, 31
	s_ashr_i32 s8, s8, 5
	s_sub_i32 s2, s2, s15
	s_add_i32 s8, s8, s10
	s_bfe_i32 s15, s2, 0x80000
	s_mul_i32 s10, s8, 0xb0
	s_bfe_u32 s15, s15, 0x3000c
	s_sub_i32 s9, s9, s10
	s_add_i32 s15, s2, s15
	s_bfe_u32 s10, s9, 0x3001c
	s_and_b32 s16, s15, 0xf8
	s_add_i32 s10, s9, s10
	s_lshl_b32 s11, s11, 3
	s_sext_i32_i8 s3, s3
	s_sub_i32 s2, s2, s16
	s_and_b32 s16, s10, 0xfff8
	s_add_i32 s24, s11, s3
	s_ashr_i32 s3, s14, 5
	s_sub_i32 s9, s9, s16
	s_lshl_b32 s3, s3, 3
	s_sext_i32_i8 s2, s2
	s_add_i32 s14, s3, s2
	s_lshl_b32 s2, s8, 3
	s_sext_i32_i16 s3, s10
	s_sext_i32_i16 s8, s9
	s_add_i32 s8, s2, s8
	s_ashr_i32 s2, s3, 3
	s_abs_i32 s16, s19
	v_writelane_b32 v254, s2, 14
	s_lshr_b32 s2, s3, 3
	v_cvt_f32_u32_e32 v1, s16
	s_bfe_i64 s[2:3], s[2:3], 0x100000
	s_lshl_b64 s[2:3], s[2:3], 19
	s_bfe_i32 s12, s12, 0x80000
	v_writelane_b32 v254, s2, 15
	s_sext_i32_i16 s12, s12
	v_rcp_iflag_f32_e32 v1, v1
	v_writelane_b32 v254, s3, 16
	s_lshl_b32 s2, s7, 4
	v_writelane_b32 v254, s2, 17
	s_ashr_i32 s2, s12, 3
	v_writelane_b32 v254, s2, 18
	s_lshr_b32 s2, s12, 3
	s_bfe_i64 s[2:3], s[2:3], 0x100000
	s_bfe_i32 s11, s15, 0x80000
	s_lshl_b64 s[2:3], s[2:3], 19
	v_mul_f32_e32 v1, 0x4f7ffffe, v1
	s_sext_i32_i16 s11, s11
	v_writelane_b32 v254, s2, 19
	v_cvt_u32_f32_e32 v1, v1
	s_sub_i32 s17, 0, s16
	v_writelane_b32 v254, s3, 20
	s_ashr_i32 s2, s11, 3
	v_writelane_b32 v254, s2, 21
	s_lshr_b32 s2, s11, 3
	s_bfe_i64 s[2:3], s[2:3], 0x100000
	s_lshl_b64 s[2:3], s[2:3], 19
	v_readfirstlane_b32 s18, v1
	v_writelane_b32 v254, s2, 22
	s_mul_i32 s17, s17, s18
	s_mul_hi_u32 s17, s18, s17
	v_writelane_b32 v254, s3, 23
	v_writelane_b32 v254, s23, 24
	s_lshl_b32 s3, s23, 1
	s_add_i32 s18, s18, s17
	s_abs_i32 s17, s6
	s_ashr_i32 s2, s6, 31
	v_writelane_b32 v254, s3, 25
	s_mov_b32 s6, s8
	s_ashr_i32 s9, s8, 31
	v_writelane_b32 v254, s6, 26
	s_ashr_i32 s25, s24, 31
	s_mul_hi_u32 s18, s17, s18
	v_writelane_b32 v254, s7, 27
	s_lshl_b64 s[6:7], s[8:9], 19
	v_writelane_b32 v254, s6, 28
	s_mul_i32 s18, s18, s16
	s_sub_i32 s17, s17, s18
	v_writelane_b32 v254, s7, 29
	s_mov_b32 s6, s24
	v_writelane_b32 v254, s6, 30
	s_ashr_i32 s15, s14, 31
	s_sub_i32 s3, s17, s16
	v_writelane_b32 v254, s7, 31
	s_lshl_b64 s[6:7], s[24:25], 19
	v_writelane_b32 v254, s6, 32
	v_mbcnt_lo_u32_b32 v1, -1, 0
	v_mbcnt_hi_u32_b32 v218, -1, v1
	v_writelane_b32 v254, s7, 33
	s_mov_b32 s6, s14
	v_writelane_b32 v254, s6, 34
	s_movk_i32 s12, 0x2810
	s_nop 0
	v_writelane_b32 v254, s7, 35
	s_lshl_b64 s[6:7], s[14:15], 19
	s_cmp_ge_u32 s17, s16
	v_writelane_b32 v254, s6, 36
	s_cselect_b32 s3, s3, s17
	s_nop 0
	v_writelane_b32 v254, s7, 37
	s_sub_i32 s6, s3, s16
	s_cmp_ge_u32 s3, s16
	s_cselect_b32 s3, s6, s3
	s_xor_b32 s3, s3, s2
	s_sub_i32 s3, s3, s2
	s_mul_i32 s2, s4, 0x4400
	v_writelane_b32 v254, s2, 38
	s_mul_i32 s2, s4, 0x2200
	s_cmp_lt_i32 s3, 64
	v_writelane_b32 v254, s2, 39
	s_cselect_b64 s[6:7], -1, 0
	v_writelane_b32 v254, s6, 40
	s_ashr_i32 s2, s3, 31
	s_mov_b64 s[16:17], 0x80
	v_writelane_b32 v254, s7, 41
	v_writelane_b32 v254, s2, 42
	s_lshr_b32 s2, s2, 29
	s_add_i32 s2, s3, s2
	s_ashr_i32 s4, s2, 3
	s_and_b32 s2, s2, -8
	s_sub_i32 s2, s3, s2
	v_writelane_b32 v254, s4, 43
	s_cmp_gt_i32 s2, -1
	v_writelane_b32 v254, s3, 44
	s_cselect_b64 s[6:7], -1, 0
	v_writelane_b32 v254, s6, 45
	s_lshl_b32 s3, s2, 3
	s_mul_i32 s2, s2, 9
	v_writelane_b32 v254, s7, 46
	v_writelane_b32 v254, s3, 47
	s_bitcmp1_b32 s20, 0
	v_writelane_b32 v254, s2, 48
	s_cselect_b64 s[2:3], -1, 0
	v_writelane_b32 v254, s2, 49
	s_bitcmp1_b32 s19, 0
	s_movk_i32 s20, 0x7fff
	v_writelane_b32 v254, s3, 50
	s_cselect_b64 s[2:3], -1, 0
	v_writelane_b32 v254, s2, 51
	s_add_i32 s1, s1, 0x8800
	s_lshl_b32 s0, s0, 1
	v_writelane_b32 v254, s3, 52
	v_writelane_b32 v254, s1, 53
	s_add_i32 s1, s5, 0
	s_addk_i32 s1, 0x3600
	v_writelane_b32 v254, s1, 54
	s_add_i32 s1, s21, 0xcc00
	v_writelane_b32 v254, s1, 55
	v_writelane_b32 v254, s21, 56
	s_add_i32 s1, s21, 0x8800
	v_writelane_b32 v254, s1, 57
	v_writelane_b32 v254, s22, 58
	s_xor_b32 s1, s22, 3
	v_writelane_b32 v254, s1, 59
	s_mov_b32 s1, 0x3e4ccccd
	v_writelane_b32 v254, s1, 60
	s_add_i32 s1, 0, 0x24160
	v_writelane_b32 v254, s1, 61
	s_add_i32 s1, 0, 0x24164
	v_writelane_b32 v254, s1, 62
	s_add_i32 s1, 0, 0x11004
	v_writelane_b32 v254, s1, 63
	s_add_i32 s1, 0, 0x11000
	v_writelane_b32 v255, s1, 0
	s_add_i32 s1, 0, 0x870
	v_writelane_b32 v255, s1, 1
	s_add_i32 s1, 0, 0xc570
	v_writelane_b32 v255, s1, 2
	s_add_i32 s1, 0, 0x19800
	v_writelane_b32 v255, s1, 3
	v_writelane_b32 v255, s0, 4
	s_movk_i32 s2, 0x2000
	s_movk_i32 s21, 0x84
	v_writelane_b32 v255, s1, 5
	s_add_i32 s0, 0, 0x48c0
	v_writelane_b32 v255, s0, 6
	s_mov_b64 s[0:1], 0
	v_writelane_b32 v255, s0, 7
	s_movk_i32 s3, 0x2c00
	s_nop 0
	v_writelane_b32 v255, s1, 8
	s_mov_b64 s[0:1], -1
	v_writelane_b32 v255, s0, 9
	s_nop 1
	v_writelane_b32 v255, s1, 10
	s_mov_b32 s0, 1.0
	v_writelane_b32 v255, s0, 11
	s_nop 1
	v_writelane_b32 v255, s1, 12
	s_branch .LBB0_81

.LBB0_256:
	v_readlane_b32 s0, v255, 13
	v_readlane_b32 s4, v252, 7
	s_add_i32 s10, s0, 2
	v_readlane_b32 s7, v252, 10
	s_cmp_ge_i32 s10, s7
	s_barrier
	v_readlane_b32 s5, v252, 8
	v_readlane_b32 s6, v252, 9
	s_cbranch_scc1 .LBB0_310
	v_readlane_b32 s74, v255, 62
	s_nop 3
	s_cmp_eq_u32 s74, 0
	s_cbranch_scc1 .Lglob_a
	s_waitcnt vmcnt(0) lgkmcnt(0)
	s_barrier
	s_mov_b64 s[76:77], exec
	v_readlane_b32 s78, v252, 11
	v_readlane_b32 s79, v252, 12
	s_nop 3
	s_and_b64 s[78:79], s[76:77], s[78:79]
	s_mov_b64 exec, s[78:79]
	s_cbranch_execz .Lloc_done_a
	v_readlane_b32 s80, v253, 26
	v_readlane_b32 s81, v253, 27
	v_readlane_b32 s82, v255, 13
	s_nop 3
	s_add_u32 s80, s80, 0x2300
	s_addc_u32 s81, s81, 0
	s_cmp_lg_u32 s82, 0
	s_cselect_b32 s82, 0x40, 0
	s_add_i32 s82, s82, 32
	s_mov_b32 s84, 0
	v_mov_b32_e32 v1, 1
	s_nop 1
	global_atomic_add v3, v1, s[80:81]
.Lloc_spin_a:
	global_load_dword v2, v3, s[80:81] sc1
	s_waitcnt vmcnt(0)
	v_readfirstlane_b32 s83, v2
	s_nop 3
	s_cmp_ge_u32 s83, s82
	s_cbranch_scc1 .Lloc_rel_a
	s_add_i32 s84, s84, 1
	s_cmp_gt_u32 s84, 0x40000
	s_cbranch_scc1 .Lloc_rel_a
	s_sleep 1
	s_branch .Lloc_spin_a
.Lloc_rel_a:
	buffer_inv sc1
	s_waitcnt vmcnt(0)
.Lloc_done_a:
	s_mov_b64 exec, s[76:77]
	s_barrier
	s_branch .LBB0_310
.Lglob_a:
	s_waitcnt vmcnt(0)
	s_barrier
	s_mov_b64 s[0:1], exec
	v_readlane_b32 s4, v252, 11
	v_readlane_b32 s5, v252, 12
	s_and_b64 s[4:5], s[0:1], s[4:5]
	s_mov_b64 exec, s[4:5]
	s_cbranch_execz .LBB0_309
	v_readlane_b32 s4, v254, 61
	s_waitcnt vmcnt(0) expcnt(0) lgkmcnt(0)
	s_nop 0
	v_mov_b32_e32 v1, s4
	ds_read_b32 v4, v1
	v_readlane_b32 s4, v254, 62
	s_waitcnt lgkmcnt(0)
	v_cmp_ne_u32_e32 vcc, 0, v4
	v_mov_b32_e32 v1, s4
	ds_read_b32 v2, v1
	s_cbranch_vccnz .LBB0_273
	v_readlane_b32 s6, v252, 2
	v_readlane_b32 s7, v252, 3
	s_load_dwordx2 s[4:5], s[6:7], 0x4
	v_readlane_b32 s6, v252, 4
	s_mov_b32 s14, 1
	s_waitcnt lgkmcnt(0)
	s_mul_i32 s11, s4, s6
	s_mul_i32 s11, s11, s5
	s_branch .LBB0_261

.LBB0_397:
	v_readlane_b32 s0, v255, 13
	v_readlane_b32 s4, v252, 7
	s_add_i32 s10, s0, 3
	v_readlane_b32 s7, v252, 10
	s_cmp_lt_i32 s10, s7
	v_readlane_b32 s5, v252, 8
	v_readlane_b32 s6, v252, 9
	s_cbranch_scc0 .LBB0_451
	v_readlane_b32 s74, v255, 62
	s_nop 3
	s_cmp_eq_u32 s74, 0
	s_cbranch_scc1 .Lglob_b
	s_waitcnt vmcnt(0) lgkmcnt(0)
	s_barrier
	s_mov_b64 s[76:77], exec
	v_readlane_b32 s78, v252, 11
	v_readlane_b32 s79, v252, 12
	s_nop 3
	s_and_b64 s[78:79], s[76:77], s[78:79]
	s_mov_b64 exec, s[78:79]
	s_cbranch_execz .Lloc_done_b
	v_readlane_b32 s80, v253, 26
	v_readlane_b32 s81, v253, 27
	v_readlane_b32 s82, v255, 13
	s_nop 3
	s_add_u32 s80, s80, 0x2300
	s_addc_u32 s81, s81, 0
	s_cmp_lg_u32 s82, 0
	s_cselect_b32 s82, 0x40, 0
	s_add_i32 s82, s82, 64
	s_mov_b32 s84, 0
	v_mov_b32_e32 v1, 1
	s_nop 1
	global_atomic_add v3, v1, s[80:81]

.LBB0_625:
	v_mul_f32_e32 v4, v61, v61
	v_pk_fma_f32 v[4:5], v[60:61], v[60:61], v[4:5] op_sel_hi:[1,1,0]
	v_mul_f32_e32 v6, v65, v65
	v_pk_fma_f32 v[4:5], v[64:65], v[64:65], v[4:5]
	s_mov_b32 s4, 0xf800000
	v_pk_add_f32 v[4:5], v[4:5], v[6:7] op_sel_hi:[1,0]
	v_mul_f32_e32 v6, v63, v63
	v_pk_fma_f32 v[4:5], v[62:63], v[62:63], v[4:5]
	s_mov_b32 s19, s35
	v_pk_add_f32 v[4:5], v[4:5], v[6:7] op_sel_hi:[1,0]
	v_mul_f32_e32 v6, v67, v67
	v_pk_fma_f32 v[4:5], v[66:67], v[66:67], v[4:5]
	v_ashrrev_i32_e32 v167, 31, v166
	v_pk_add_f32 v[4:5], v[4:5], v[6:7] op_sel_hi:[1,0]
	v_mul_f32_e32 v6, v57, v57
	v_pk_fma_f32 v[4:5], v[56:57], v[56:57], v[4:5]
	v_ashrrev_i32_e32 v165, 31, v164
	v_pk_add_f32 v[4:5], v[4:5], v[6:7] op_sel_hi:[1,0]
	v_mul_f32_e32 v6, v59, v59
	v_pk_fma_f32 v[4:5], v[58:59], v[58:59], v[4:5]
	v_ashrrev_i32_e32 v163, 31, v162
	v_pk_add_f32 v[4:5], v[4:5], v[6:7] op_sel_hi:[1,0]
	v_mul_f32_e32 v6, v47, v47
	v_pk_fma_f32 v[4:5], v[46:47], v[46:47], v[4:5]
	v_ashrrev_i32_e32 v161, 31, v160
	v_pk_add_f32 v[4:5], v[4:5], v[6:7] op_sel_hi:[1,0]
	v_mul_f32_e32 v6, v55, v55
	v_pk_fma_f32 v[4:5], v[54:55], v[54:55], v[4:5]
	s_nop 0
	v_pk_add_f32 v[4:5], v[4:5], v[6:7] op_sel_hi:[1,0]
	v_mul_f32_e32 v6, v39, v39
	v_pk_fma_f32 v[4:5], v[38:39], v[38:39], v[4:5]
	s_nop 0
	v_pk_add_f32 v[4:5], v[4:5], v[6:7] op_sel_hi:[1,0]
	v_mul_f32_e32 v6, v41, v41
	v_pk_fma_f32 v[4:5], v[40:41], v[40:41], v[4:5]
	s_nop 0
	v_pk_add_f32 v[4:5], v[4:5], v[6:7] op_sel_hi:[1,0]
	v_mul_f32_e32 v6, v37, v37
	v_pk_fma_f32 v[4:5], v[36:37], v[36:37], v[4:5]
	s_nop 0
	v_pk_add_f32 v[4:5], v[4:5], v[6:7] op_sel_hi:[1,0]
	v_mul_f32_e32 v6, v43, v43
	v_pk_fma_f32 v[4:5], v[42:43], v[42:43], v[4:5]
	s_nop 0
	v_pk_add_f32 v[4:5], v[4:5], v[6:7] op_sel_hi:[1,0]
	v_mul_f32_e32 v6, v49, v49
	v_pk_fma_f32 v[4:5], v[48:49], v[48:49], v[4:5]
	s_nop 0
	v_pk_add_f32 v[4:5], v[4:5], v[6:7] op_sel_hi:[1,0]
	v_mul_f32_e32 v6, v51, v51
	v_pk_fma_f32 v[4:5], v[50:51], v[50:51], v[4:5]
	s_nop 0
	v_pk_add_f32 v[4:5], v[4:5], v[6:7] op_sel_hi:[1,0]
	v_mul_f32_e32 v6, v45, v45
	v_pk_fma_f32 v[4:5], v[44:45], v[44:45], v[4:5]
	s_nop 0
	v_pk_add_f32 v[4:5], v[4:5], v[6:7] op_sel_hi:[1,0]
	ds_read_b32 v6, v84 offset:7936
	s_waitcnt lgkmcnt(0)
	v_fma_f32 v2, v2, v19, -v6
	v_cndmask_b32_e64 v53, -v2, v2, s[38:39]
	v_pk_fma_f32 v[4:5], v[52:53], v[52:53], v[4:5]
	v_mul_f32_e32 v2, v53, v53
	v_pk_add_f32 v[4:5], v[4:5], v[2:3] op_sel_hi:[1,0]
	s_nop 0
	v_mov_b32_e32 v2, v4
	s_nop 1
	v_permlane32_swap_b32_e32 v4, v2
	v_add_f32_e32 v2, v4, v2
	v_fmamk_f32 v2, v2, 0x3c800000, v215
	v_cmp_gt_f32_e32 vcc, s4, v2
	v_mul_f32_e32 v4, 0x4f800000, v2
	s_nop 0
	v_cndmask_b32_e32 v2, v2, v4, vcc
	v_sqrt_f32_e32 v4, v2
	s_nop 0
	v_add_u32_e32 v5, -1, v4
	v_fma_f32 v6, -v5, v4, v2
	v_cmp_ge_f32_e64 s[4:5], 0, v6
	v_add_u32_e32 v6, 1, v4
	s_nop 0
	v_cndmask_b32_e64 v5, v4, v5, s[4:5]
	v_fma_f32 v4, -v6, v4, v2
	v_cmp_lt_f32_e64 s[4:5], 0, v4
	s_nop 1
	v_cndmask_b32_e64 v4, v5, v6, s[4:5]
	v_mul_f32_e32 v5, 0x37800000, v4
	v_cndmask_b32_e32 v4, v4, v5, vcc
	v_cmp_class_f32_e32 vcc, v2, v216
	s_nop 1
	v_cndmask_b32_e32 v2, v4, v2, vcc
	v_div_scale_f32 v4, s[4:5], v2, v2, v1
	v_rcp_f32_e32 v5, v4
	s_mov_b64 s[4:5], 0xb300600
	v_fma_f32 v6, -v4, v5, 1.0
	v_fmac_f32_e32 v5, v6, v5
	v_div_scale_f32 v6, vcc, v1, v2, v1
	v_mul_f32_e32 v7, v6, v5
	v_fma_f32 v8, -v4, v7, v6
	v_fmac_f32_e32 v7, v8, v5
	v_fma_f32 v4, -v4, v7, v6
	v_div_fmas_f32 v4, v4, v5, v7
	v_div_fixup_f32 v2, v4, v2, v1
	v_lshlrev_b64 v[4:5], 11, v[156:157]
	v_lshl_add_u64 v[4:5], s[26:27], 0, v[4:5]
	v_lshl_add_u64 v[4:5], v[4:5], 0, s[18:19]
	v_lshl_add_u64 v[8:9], v[4:5], 0, s[4:5]
	s_load_dwordx2 s[4:5], s[22:23], 0xa0
	v_pk_mul_f32 v[12:13], v[60:61], v[2:3] op_sel_hi:[1,0]
	s_waitcnt lgkmcnt(0)
	s_add_u32 s4, s4, s24
	s_addc_u32 s5, s5, s25
	v_lshl_add_u64 v[10:11], v[166:167], 2, s[4:5]
	global_load_dwordx4 v[4:7], v[10:11], off
	global_load_dwordx4 v[114:117], v[10:11], off offset:32
	global_load_dwordx4 v[118:121], v[10:11], off offset:64
	global_load_dwordx4 v[122:125], v[10:11], off offset:96
	global_load_dwordx4 v[126:129], v[10:11], off offset:128
	global_load_dwordx4 v[130:133], v[10:11], off offset:160
	global_load_dwordx4 v[134:137], v[10:11], off offset:192
	global_load_dwordx4 v[138:141], v[10:11], off offset:224
	s_waitcnt vmcnt(7)
	v_pk_mul_f32 v[4:5], v[4:5], v[12:13]
	s_nop 0
	v_cvt_pk_bf16_f32 v12, v4, v5
	v_pk_mul_f32 v[4:5], v[64:65], v[2:3] op_sel_hi:[1,0]
	s_nop 0
	v_pk_mul_f32 v[4:5], v[6:7], v[4:5]
	v_lshl_add_u64 v[6:7], v[164:165], 2, s[4:5]
	v_cvt_pk_bf16_f32 v13, v4, v5
	v_lshl_add_u64 v[4:5], v[166:167], 1, v[8:9]
	global_store_dwordx2 v[4:5], v[12:13], off
	v_pk_mul_f32 v[6:7], v[62:63], v[2:3] op_sel_hi:[1,0]
	s_waitcnt vmcnt(7)
	v_mov_b64_e32 v[12:13], v[114:115]
	v_mov_b64_e32 v[14:15], v[116:117]
	v_pk_mul_f32 v[6:7], v[12:13], v[6:7]
	v_pk_mul_f32 v[12:13], v[66:67], v[2:3] op_sel_hi:[1,0]
	v_cvt_pk_bf16_f32 v6, v6, v7
	v_pk_mul_f32 v[12:13], v[14:15], v[12:13]
	s_nop 0
	v_cvt_pk_bf16_f32 v7, v12, v13
	v_lshl_add_u64 v[12:13], v[164:165], 1, v[8:9]
	global_store_dwordx2 v[12:13], v[6:7], off
	v_lshl_add_u64 v[6:7], v[162:163], 2, s[4:5]
	v_pk_mul_f32 v[6:7], v[56:57], v[2:3] op_sel_hi:[1,0]
	s_waitcnt vmcnt(7)
	v_mov_b64_e32 v[12:13], v[118:119]
	v_mov_b64_e32 v[14:15], v[120:121]
	v_pk_mul_f32 v[6:7], v[12:13], v[6:7]
	v_pk_mul_f32 v[12:13], v[58:59], v[2:3] op_sel_hi:[1,0]
	v_cvt_pk_bf16_f32 v6, v6, v7
	v_pk_mul_f32 v[12:13], v[14:15], v[12:13]
	s_nop 0
	v_cvt_pk_bf16_f32 v7, v12, v13
	v_lshl_add_u64 v[12:13], v[162:163], 1, v[8:9]
	global_store_dwordx2 v[12:13], v[6:7], off
	v_lshl_add_u64 v[6:7], v[160:161], 2, s[4:5]
	v_pk_mul_f32 v[6:7], v[46:47], v[2:3] op_sel_hi:[1,0]
	v_lshl_add_u64 v[8:9], v[160:161], 1, v[8:9]
	v_readlane_b32 s4, v252, 4
	s_add_i32 s14, s14, s4
	s_add_i32 s11, s11, s4
	s_cmpk_gt_i32 s14, 0xff
	s_waitcnt vmcnt(7)
	v_mov_b64_e32 v[12:13], v[122:123]
	v_mov_b64_e32 v[14:15], v[124:125]
	v_pk_mul_f32 v[6:7], v[6:7], v[12:13]
	v_pk_mul_f32 v[12:13], v[54:55], v[2:3] op_sel_hi:[1,0]
	v_cvt_pk_bf16_f32 v6, v6, v7
	v_pk_mul_f32 v[12:13], v[12:13], v[14:15]
	s_nop 0
	v_cvt_pk_bf16_f32 v7, v12, v13
	global_store_dwordx2 v[8:9], v[6:7], off
	v_pk_mul_f32 v[12:13], v[38:39], v[2:3] op_sel_hi:[1,0]
	s_waitcnt vmcnt(7)
	v_mov_b64_e32 v[6:7], v[126:127]
	v_mov_b64_e32 v[8:9], v[128:129]
	v_pk_mul_f32 v[6:7], v[12:13], v[6:7]
	v_pk_mul_f32 v[12:13], v[40:41], v[2:3] op_sel_hi:[1,0]
	v_cvt_pk_bf16_f32 v6, v6, v7
	v_pk_mul_f32 v[8:9], v[12:13], v[8:9]
	v_pk_mul_f32 v[12:13], v[36:37], v[2:3] op_sel_hi:[1,0]
	v_cvt_pk_bf16_f32 v7, v8, v9
	global_store_dwordx2 v[4:5], v[6:7], off offset:64
	s_waitcnt vmcnt(7)
	v_mov_b64_e32 v[6:7], v[130:131]
	v_mov_b64_e32 v[8:9], v[132:133]
	v_pk_mul_f32 v[6:7], v[12:13], v[6:7]
	v_pk_mul_f32 v[12:13], v[42:43], v[2:3] op_sel_hi:[1,0]
	v_cvt_pk_bf16_f32 v6, v6, v7
	v_pk_mul_f32 v[8:9], v[12:13], v[8:9]
	v_pk_mul_f32 v[12:13], v[48:49], v[2:3] op_sel_hi:[1,0]
	v_cvt_pk_bf16_f32 v7, v8, v9
	global_store_dwordx2 v[4:5], v[6:7], off offset:80
	s_waitcnt vmcnt(7)
	v_mov_b64_e32 v[6:7], v[134:135]
	v_mov_b64_e32 v[8:9], v[136:137]
	v_pk_mul_f32 v[6:7], v[12:13], v[6:7]
	v_pk_mul_f32 v[12:13], v[50:51], v[2:3] op_sel_hi:[1,0]
	v_cvt_pk_bf16_f32 v6, v6, v7
	v_pk_mul_f32 v[8:9], v[12:13], v[8:9]
	s_nop 0
	v_cvt_pk_bf16_f32 v7, v8, v9
	global_store_dwordx2 v[4:5], v[6:7], off offset:96
	v_pk_mul_f32 v[10:11], v[44:45], v[2:3] op_sel_hi:[1,0]
	s_waitcnt vmcnt(7)
	v_mov_b64_e32 v[6:7], v[138:139]
	v_mov_b64_e32 v[8:9], v[140:141]
	v_pk_mul_f32 v[6:7], v[10:11], v[6:7]
	v_pk_mul_f32 v[10:11], v[52:53], v[2:3] op_sel_hi:[1,0]
	v_cvt_pk_bf16_f32 v6, v6, v7
	v_pk_mul_f32 v[8:9], v[10:11], v[8:9]
	s_nop 0
	v_cvt_pk_bf16_f32 v7, v8, v9
	global_store_dwordx2 v[4:5], v[6:7], off offset:112
	s_barrier
	s_cbranch_scc1 .LBB0_703

.LBB0_629:
	global_load_dwordx4 v[6:9], v3, s[58:59]
	global_load_dwordx4 v[10:13], v3, s[58:59] offset:16
	global_load_dwordx4 v[14:17], v3, s[58:59] offset:32
	global_load_dwordx4 v[18:21], v3, s[58:59] offset:48
	global_load_dwordx4 v[194:197], v3, s[58:59] offset:64
	global_load_dwordx4 v[198:201], v3, s[58:59] offset:80
	global_load_dwordx4 v[202:205], v3, s[58:59] offset:96
	global_load_dwordx4 v[206:209], v3, s[58:59] offset:112
	s_waitcnt vmcnt(0)
	v_max3_f32 v5, |v6|, |v7|, |v8|
	v_max3_f32 v5, v5, |v9|, |v10|
	v_max3_f32 v5, v5, |v11|, |v12|
	v_max3_f32 v5, v5, |v13|, |v14|
	v_max3_f32 v5, v5, |v15|, |v16|
	v_max3_f32 v5, v5, |v17|, |v18|
	v_max3_f32 v5, v5, |v19|, |v20|
	v_max3_f32 v5, v5, |v21|, |v194|
	v_max3_f32 v5, v5, |v195|, |v196|
	v_max3_f32 v5, v5, |v197|, |v198|
	v_max3_f32 v5, v5, |v199|, |v200|
	v_max3_f32 v5, v5, |v201|, |v202|
	v_max3_f32 v5, v5, |v203|, |v204|
	v_max3_f32 v5, v5, |v205|, |v206|
	v_max3_f32 v5, v5, |v207|, |v208|
	v_max_f32_e64 v5, v5, |v209|

.LBB0_685:
	s_mul_i32 s34, s30, 0x8a00
	v_add_u32_e32 v2, s34, v185
	v_add_u32_e32 v188, s34, v186
	v_add_u32_e32 v2, 0xffffff40, v2
	v_add_u32_e32 v188, 0xffffca00, v188
	v_add_u32_e32 v233, 0x2000, v2
	s_sub_i32 s34, s67, s66
	s_cmp_lt_i32 s34, 1
	s_cbranch_scc1 .Lat_e3
	s_cmp_eq_u32 s34, 1
	s_cbranch_scc1 .Lat_e2
	s_cmp_eq_u32 s34, 2
	s_cbranch_scc1 .Lat_e1
	ds_read_b128 v[152:155], v188
	ds_read_b128 v[148:151], v188 offset:32
	ds_read2_b64 v[144:147], v2 offset0:0 offset1:2
	ds_read2_b64 v[140:143], v2 offset0:4 offset1:6
	ds_read2_b64 v[136:139], v233 offset0:32 offset1:34
	ds_read2_b64 v[132:135], v233 offset0:36 offset1:38
	s_branch .Lat_t0
.Lat_e1:
	ds_read_b128 v[152:155], v188 offset:4608
	ds_read_b128 v[148:151], v188 offset:4640
	ds_read2_b64 v[238:241], v2 offset0:8 offset1:10
	ds_read2_b64 v[242:245], v2 offset0:12 offset1:14
	ds_read2_b64 v[246:249], v233 offset0:40 offset1:42
	ds_read2_b64 v[210:213], v233 offset0:44 offset1:46
	s_branch .Lat_t1
.Lat_e2:
	ds_read_b128 v[152:155], v188 offset:9216
	ds_read_b128 v[148:151], v188 offset:9248
	ds_read2_b64 v[144:147], v2 offset0:16 offset1:18
	ds_read2_b64 v[140:143], v2 offset0:20 offset1:22
	ds_read2_b64 v[136:139], v233 offset0:48 offset1:50
	ds_read2_b64 v[132:135], v233 offset0:52 offset1:54
	s_branch .Lat_t2
.Lat_e3:
	ds_read_b128 v[152:155], v188 offset:13824
	ds_read_b128 v[148:151], v188 offset:13856
	ds_read2_b64 v[238:241], v2 offset0:24 offset1:26
	ds_read2_b64 v[242:245], v2 offset0:28 offset1:30
	ds_read2_b64 v[246:249], v233 offset0:56 offset1:58
	ds_read2_b64 v[210:213], v233 offset0:60 offset1:62
.Lat_t3:
	s_mov_b32 s71, s67
	s_mov_b32 s70, s68
	s_mov_b32 s69, s31
	s_waitcnt lgkmcnt(4)
	v_mfma_f32_32x32x16_bf16 v[84:99], v[152:155], v[100:103], v[36:51]
	v_mfma_f32_32x32x16_bf16 v[84:99], v[148:151], v[104:107], v[84:99]
	s_cmp_le_u32 s71, s15
	s_cbranch_scc1 .Lat_b3
	ds_read_b128 v[152:155], v188 offset:9216
	ds_read_b128 v[148:151], v188 offset:9248
	ds_read2_b64 v[144:147], v2 offset0:16 offset1:18
	ds_read2_b64 v[140:143], v2 offset0:20 offset1:22
	ds_read2_b64 v[136:139], v233 offset0:48 offset1:50
	ds_read2_b64 v[132:135], v233 offset0:52 offset1:54
	s_cmp_lg_u32 s70, 0
	s_cbranch_scc1 .Lat_o3_nd
	s_nop 2
	v_cndmask_b32_e64 v84, v84, v232, s[4:5]
	v_cndmask_b32_e64 v85, v232, v85, s[6:7]
	v_cndmask_b32_e64 v86, v86, v232, s[8:9]
	v_cndmask_b32_e64 v87, v87, v232, s[40:41]
	v_cndmask_b32_e64 v88, v88, v232, s[42:43]
	v_cndmask_b32_e64 v89, v89, v232, s[44:45]
	v_cndmask_b32_e64 v90, v90, v232, s[46:47]
	v_cndmask_b32_e64 v91, v91, v232, s[48:49]
	v_cndmask_b32_e64 v92, v92, v232, s[50:51]
	v_cndmask_b32_e64 v93, v93, v232, s[52:53]
	v_cndmask_b32_e64 v94, v94, v232, s[54:55]
	v_cndmask_b32_e64 v95, v95, v232, s[56:57]
	v_cndmask_b32_e64 v96, v96, v232, s[58:59]
	v_cndmask_b32_e64 v97, v97, v232, s[60:61]
	v_cndmask_b32_e64 v98, v98, v232, s[62:63]
	v_cndmask_b32_e64 v99, v99, v232, s[64:65]
.Lat_o3_nd:
	s_waitcnt lgkmcnt(6)
	v_cvt_f32_i32_e32 v189, s70
	v_fma_f32 v189, v167, v189, -v184
	v_add_f32_e32 v85, v189, v85
	v_add_f32_e32 v84, v189, v84
	v_exp_f32_e32 v190, v85
	v_add_f32_e32 v85, v189, v86
	v_add_f32_e32 v86, v189, v87
	v_add_f32_e32 v87, v189, v89
	v_exp_f32_e32 v84, v84
	v_exp_f32_e32 v85, v85
	v_exp_f32_e32 v191, v86
	v_add_f32_e32 v86, v189, v88
	v_exp_f32_e32 v88, v87
	v_add_f32_e32 v87, v189, v90
	v_add_f32_e32 v89, v189, v91
	v_exp_f32_e32 v86, v86
	v_exp_f32_e32 v87, v87
	v_exp_f32_e32 v89, v89
	v_add_f32_e32 v91, v189, v93
	v_add_f32_e32 v93, v189, v95
	v_add_f32_e32 v95, v189, v97
	v_add_f32_e32 v90, v189, v92
	v_exp_f32_e32 v92, v91
	v_add_f32_e32 v91, v189, v94
	v_add_f32_e32 v94, v189, v96
	v_exp_f32_e32 v96, v95
	v_add_f32_e32 v95, v189, v98
	v_add_f32_e32 v97, v189, v99
	v_add_f32_e32 v98, 0, v84
	v_add_f32_e32 v99, 0, v85
	v_cvt_pk_bf16_f32 v84, v84, v190
	v_add_f32_e32 v98, v86, v98
	v_add_f32_e32 v99, v87, v99
	v_cvt_pk_bf16_f32 v85, v85, v191
	v_cvt_pk_bf16_f32 v86, v86, v88
	v_cvt_pk_bf16_f32 v87, v87, v89
	v_exp_f32_e32 v90, v90
	v_exp_f32_e32 v91, v91
	v_mfma_f32_32x32x16_bf16 v[52:67], v[238:241], v[84:87], v[52:67]
	v_exp_f32_e32 v93, v93
	v_exp_f32_e32 v94, v94
	v_exp_f32_e32 v95, v95
	v_exp_f32_e32 v97, v97
	v_add_f32_e32 v192, 0, v190
	v_add_f32_e32 v193, 0, v191
	v_add_f32_e32 v98, v90, v98
	v_add_f32_e32 v99, v91, v99
	v_add_f32_e32 v192, v88, v192
	v_add_f32_e32 v193, v89, v193
	v_mfma_f32_32x32x16_bf16 v[20:35], v[246:249], v[84:87], v[20:35]
	v_cvt_pk_bf16_f32 v88, v90, v92
	v_cvt_pk_bf16_f32 v89, v91, v93
	v_cvt_pk_bf16_f32 v90, v94, v96
	v_cvt_pk_bf16_f32 v91, v95, v97
	v_add_f32_e64 v192, v92, v192
	v_add_f32_e64 v193, v93, v193
	v_add_f32_e32 v98, v94, v98
	v_add_f32_e32 v99, v95, v99
	v_add_f32_e32 v192, v96, v192
	v_add_f32_e32 v193, v97, v193
	v_mfma_f32_32x32x16_bf16 v[52:67], v[242:245], v[88:91], v[52:67]
	v_add_f32_e64 v98, v98, v192
	v_add_f32_e64 v99, v99, v193
	v_add_f32_e32 v98, v98, v99
	v_add_f32_e32 v187, v187, v98
	v_mfma_f32_32x32x16_bf16 v[20:35], v[210:213], v[88:91], v[20:35]
	s_branch .Lat_t2
.Lat_b3:
	s_cmp_lg_u32 s70, 0
	s_cbranch_scc1 .Lat_b3_nd
	s_nop 8
	v_cndmask_b32_e64 v84, v84, v232, s[4:5]
	v_cndmask_b32_e64 v85, v232, v85, s[6:7]
	v_cndmask_b32_e64 v86, v86, v232, s[8:9]
	v_cndmask_b32_e64 v87, v87, v232, s[40:41]
	v_cndmask_b32_e64 v88, v88, v232, s[42:43]
	v_cndmask_b32_e64 v89, v89, v232, s[44:45]
	v_cndmask_b32_e64 v90, v90, v232, s[46:47]
	v_cndmask_b32_e64 v91, v91, v232, s[48:49]
	v_cndmask_b32_e64 v92, v92, v232, s[50:51]
	v_cndmask_b32_e64 v93, v93, v232, s[52:53]
	v_cndmask_b32_e64 v94, v94, v232, s[54:55]
	v_cndmask_b32_e64 v95, v95, v232, s[56:57]
	v_cndmask_b32_e64 v96, v96, v232, s[58:59]
	v_cndmask_b32_e64 v97, v97, v232, s[60:61]
	v_cndmask_b32_e64 v98, v98, v232, s[62:63]
	v_cndmask_b32_e64 v99, v99, v232, s[64:65]
.Lat_b3_nd:
	s_waitcnt lgkmcnt(0)
	v_cvt_f32_i32_e32 v189, s70
	v_fma_f32 v189, v167, v189, -v184
	s_nop 5
	v_add_f32_e32 v85, v189, v85
	v_add_f32_e32 v84, v189, v84
	v_exp_f32_e32 v190, v85
	v_add_f32_e32 v85, v189, v86
	v_add_f32_e32 v86, v189, v87
	v_add_f32_e32 v87, v189, v89
	v_exp_f32_e32 v84, v84
	v_exp_f32_e32 v85, v85
	v_exp_f32_e32 v191, v86
	v_add_f32_e32 v86, v189, v88
	v_exp_f32_e32 v88, v87
	v_add_f32_e32 v87, v189, v90
	v_add_f32_e32 v89, v189, v91
	v_exp_f32_e32 v86, v86
	v_exp_f32_e32 v87, v87
	v_exp_f32_e32 v89, v89
	v_add_f32_e32 v91, v189, v93
	v_add_f32_e32 v93, v189, v95
	v_add_f32_e32 v95, v189, v97
	v_add_f32_e32 v90, v189, v92
	v_exp_f32_e32 v92, v91
	v_add_f32_e32 v91, v189, v94
	v_add_f32_e32 v94, v189, v96
	v_exp_f32_e32 v96, v95
	v_add_f32_e32 v95, v189, v98
	v_add_f32_e32 v97, v189, v99
	v_add_f32_e32 v98, 0, v84
	v_add_f32_e32 v99, 0, v85
	v_cvt_pk_bf16_f32 v84, v84, v190
	v_add_f32_e32 v98, v86, v98
	v_add_f32_e32 v99, v87, v99
	v_cvt_pk_bf16_f32 v85, v85, v191
	v_cvt_pk_bf16_f32 v86, v86, v88
	v_cvt_pk_bf16_f32 v87, v87, v89
	v_exp_f32_e32 v90, v90
	v_exp_f32_e32 v91, v91
	v_mfma_f32_32x32x16_bf16 v[52:67], v[238:241], v[84:87], v[52:67]
	v_exp_f32_e32 v93, v93
	v_exp_f32_e32 v94, v94
	v_exp_f32_e32 v95, v95
	v_exp_f32_e32 v97, v97
	v_add_f32_e32 v192, 0, v190
	v_add_f32_e32 v193, 0, v191
	v_add_f32_e32 v98, v90, v98
	v_add_f32_e32 v99, v91, v99
	v_add_f32_e32 v192, v88, v192
	v_add_f32_e32 v193, v89, v193
	v_mfma_f32_32x32x16_bf16 v[20:35], v[246:249], v[84:87], v[20:35]
	v_cvt_pk_bf16_f32 v88, v90, v92
	v_cvt_pk_bf16_f32 v89, v91, v93
	v_cvt_pk_bf16_f32 v90, v94, v96
	v_cvt_pk_bf16_f32 v91, v95, v97
	v_add_f32_e64 v192, v92, v192
	v_add_f32_e64 v193, v93, v193
	v_add_f32_e32 v98, v94, v98
	v_add_f32_e32 v99, v95, v99
	v_add_f32_e32 v192, v96, v192
	v_add_f32_e32 v193, v97, v193
	v_mfma_f32_32x32x16_bf16 v[52:67], v[242:245], v[88:91], v[52:67]
	v_add_f32_e64 v98, v98, v192
	v_add_f32_e64 v99, v99, v193
	v_add_f32_e32 v98, v98, v99
	v_add_f32_e32 v187, v187, v98
	v_mfma_f32_32x32x16_bf16 v[20:35], v[210:213], v[88:91], v[20:35]
	v_mfma_f32_32x32x16_bf16 v[84:99], v[152:155], v[108:111], v[36:51]
	v_mfma_f32_32x32x16_bf16 v[84:99], v[148:151], v[112:115], v[84:99]
	ds_read_b128 v[152:155], v188 offset:9216
	ds_read_b128 v[148:151], v188 offset:9248
	ds_read2_b64 v[144:147], v2 offset0:16 offset1:18
	ds_read2_b64 v[140:143], v2 offset0:20 offset1:22
	ds_read2_b64 v[136:139], v233 offset0:48 offset1:50
	ds_read2_b64 v[132:135], v233 offset0:52 offset1:54
	s_cmp_lg_u32 s69, 0
	s_cbranch_scc1 .Lat_b3_nd1
	s_nop 4
	v_cndmask_b32_e64 v84, v84, v232, s[4:5]
	v_cndmask_b32_e64 v85, v232, v85, s[6:7]
	v_cndmask_b32_e64 v86, v86, v232, s[8:9]
	v_cndmask_b32_e64 v87, v87, v232, s[40:41]
	v_cndmask_b32_e64 v88, v88, v232, s[42:43]
	v_cndmask_b32_e64 v89, v89, v232, s[44:45]
	v_cndmask_b32_e64 v90, v90, v232, s[46:47]
	v_cndmask_b32_e64 v91, v91, v232, s[48:49]
	v_cndmask_b32_e64 v92, v92, v232, s[50:51]
	v_cndmask_b32_e64 v93, v93, v232, s[52:53]
	v_cndmask_b32_e64 v94, v94, v232, s[54:55]
	v_cndmask_b32_e64 v95, v95, v232, s[56:57]
	v_cndmask_b32_e64 v96, v96, v232, s[58:59]
	v_cndmask_b32_e64 v97, v97, v232, s[60:61]
	v_cndmask_b32_e64 v98, v98, v232, s[62:63]
	v_cndmask_b32_e64 v99, v99, v232, s[64:65]
.Lat_b3_nd1:
	v_cvt_f32_i32_e32 v234, s69
	v_fma_f32 v236, v167, v234, -v177
	s_nop 2
	v_add_f32_e32 v85, v236, v85
	v_add_f32_e32 v84, v236, v84
	v_exp_f32_e32 v234, v85
	v_add_f32_e32 v85, v236, v86
	v_add_f32_e32 v86, v236, v87
	v_add_f32_e32 v87, v236, v89
	v_exp_f32_e32 v84, v84
	v_exp_f32_e32 v85, v85
	v_exp_f32_e32 v235, v86
	v_add_f32_e32 v86, v236, v88
	v_exp_f32_e32 v88, v87
	v_add_f32_e32 v87, v236, v90
	v_add_f32_e32 v89, v236, v91
	v_exp_f32_e32 v86, v86
	v_exp_f32_e32 v87, v87
	v_exp_f32_e32 v89, v89
	v_add_f32_e32 v91, v236, v93
	v_add_f32_e32 v93, v236, v95
	v_add_f32_e32 v95, v236, v97
	v_add_f32_e32 v90, v236, v92
	v_exp_f32_e32 v92, v91
	v_add_f32_e32 v91, v236, v94
	v_add_f32_e32 v94, v236, v96
	v_exp_f32_e32 v96, v95
	v_add_f32_e32 v95, v236, v98
	v_add_f32_e32 v97, v236, v99
	v_add_f32_e32 v98, 0, v84
	v_add_f32_e32 v99, 0, v85
	v_cvt_pk_bf16_f32 v84, v84, v234
	v_add_f32_e32 v98, v86, v98
	v_add_f32_e32 v99, v87, v99
	v_cvt_pk_bf16_f32 v85, v85, v235
	v_cvt_pk_bf16_f32 v86, v86, v88
	v_cvt_pk_bf16_f32 v87, v87, v89
	v_exp_f32_e32 v90, v90
	v_exp_f32_e32 v91, v91
	v_mfma_f32_32x32x16_bf16 v[68:83], v[238:241], v[84:87], v[68:83]
	v_exp_f32_e32 v93, v93
	v_exp_f32_e32 v94, v94
	v_exp_f32_e32 v95, v95
	v_exp_f32_e32 v97, v97
	v_add_f32_e32 v236, 0, v234
	v_add_f32_e32 v237, 0, v235
	v_add_f32_e32 v98, v90, v98
	v_add_f32_e32 v99, v91, v99
	v_add_f32_e32 v236, v88, v236
	v_add_f32_e32 v237, v89, v237
	v_mfma_f32_32x32x16_bf16 v[4:19], v[246:249], v[84:87], v[4:19]
	v_cvt_pk_bf16_f32 v88, v90, v92
	v_cvt_pk_bf16_f32 v89, v91, v93
	v_cvt_pk_bf16_f32 v90, v94, v96
	v_cvt_pk_bf16_f32 v91, v95, v97
	v_add_f32_e64 v236, v92, v236
	v_add_f32_e64 v237, v93, v237
	v_add_f32_e32 v98, v94, v98
	v_add_f32_e32 v99, v95, v99
	v_add_f32_e32 v236, v96, v236
	v_add_f32_e32 v237, v97, v237
	v_mfma_f32_32x32x16_bf16 v[68:83], v[242:245], v[88:91], v[68:83]
	v_add_f32_e64 v98, v98, v236
	v_add_f32_e64 v99, v99, v237
	v_add_f32_e32 v98, v98, v99
	v_add_f32_e32 v183, v183, v98
	v_mfma_f32_32x32x16_bf16 v[4:19], v[210:213], v[88:91], v[4:19]
.Lat_t2:
	s_sub_i32 s71, s67, 1
	s_sub_i32 s70, s68, 1
	s_sub_i32 s69, s31, 1
	s_waitcnt lgkmcnt(4)
	v_mfma_f32_32x32x16_bf16 v[84:99], v[152:155], v[100:103], v[36:51]
	v_mfma_f32_32x32x16_bf16 v[84:99], v[148:151], v[104:107], v[84:99]
	s_cmp_le_u32 s71, s15
	s_cbranch_scc1 .Lat_b2
	ds_read_b128 v[152:155], v188 offset:4608
	ds_read_b128 v[148:151], v188 offset:4640
	ds_read2_b64 v[238:241], v2 offset0:8 offset1:10
	ds_read2_b64 v[242:245], v2 offset0:12 offset1:14
	ds_read2_b64 v[246:249], v233 offset0:40 offset1:42
	ds_read2_b64 v[210:213], v233 offset0:44 offset1:46
	s_cmp_lg_u32 s70, 0
	s_cbranch_scc1 .Lat_o2_nd
	s_nop 2
	v_cndmask_b32_e64 v84, v84, v232, s[4:5]
	v_cndmask_b32_e64 v85, v232, v85, s[6:7]
	v_cndmask_b32_e64 v86, v86, v232, s[8:9]
	v_cndmask_b32_e64 v87, v87, v232, s[40:41]
	v_cndmask_b32_e64 v88, v88, v232, s[42:43]
	v_cndmask_b32_e64 v89, v89, v232, s[44:45]
	v_cndmask_b32_e64 v90, v90, v232, s[46:47]
	v_cndmask_b32_e64 v91, v91, v232, s[48:49]
	v_cndmask_b32_e64 v92, v92, v232, s[50:51]
	v_cndmask_b32_e64 v93, v93, v232, s[52:53]
	v_cndmask_b32_e64 v94, v94, v232, s[54:55]
	v_cndmask_b32_e64 v95, v95, v232, s[56:57]
	v_cndmask_b32_e64 v96, v96, v232, s[58:59]
	v_cndmask_b32_e64 v97, v97, v232, s[60:61]
	v_cndmask_b32_e64 v98, v98, v232, s[62:63]
	v_cndmask_b32_e64 v99, v99, v232, s[64:65]
.Lat_o2_nd:
	s_waitcnt lgkmcnt(6)
	v_cvt_f32_i32_e32 v189, s70
	v_fma_f32 v189, v167, v189, -v184
	v_add_f32_e32 v85, v189, v85
	v_add_f32_e32 v84, v189, v84
	v_exp_f32_e32 v190, v85
	v_add_f32_e32 v85, v189, v86
	v_add_f32_e32 v86, v189, v87
	v_add_f32_e32 v87, v189, v89
	v_exp_f32_e32 v84, v84
	v_exp_f32_e32 v85, v85
	v_exp_f32_e32 v191, v86
	v_add_f32_e32 v86, v189, v88
	v_exp_f32_e32 v88, v87
	v_add_f32_e32 v87, v189, v90
	v_add_f32_e32 v89, v189, v91
	v_exp_f32_e32 v86, v86
	v_exp_f32_e32 v87, v87
	v_exp_f32_e32 v89, v89
	v_add_f32_e32 v91, v189, v93
	v_add_f32_e32 v93, v189, v95
	v_add_f32_e32 v95, v189, v97
	v_add_f32_e32 v90, v189, v92
	v_exp_f32_e32 v92, v91
	v_add_f32_e32 v91, v189, v94
	v_add_f32_e32 v94, v189, v96
	v_exp_f32_e32 v96, v95
	v_add_f32_e32 v95, v189, v98
	v_add_f32_e32 v97, v189, v99
	v_add_f32_e32 v98, 0, v84
	v_add_f32_e32 v99, 0, v85
	v_cvt_pk_bf16_f32 v84, v84, v190
	v_add_f32_e32 v98, v86, v98
	v_add_f32_e32 v99, v87, v99
	v_cvt_pk_bf16_f32 v85, v85, v191
	v_cvt_pk_bf16_f32 v86, v86, v88
	v_cvt_pk_bf16_f32 v87, v87, v89
	v_exp_f32_e32 v90, v90
	v_exp_f32_e32 v91, v91
	v_mfma_f32_32x32x16_bf16 v[52:67], v[144:147], v[84:87], v[52:67]
	v_exp_f32_e32 v93, v93
	v_exp_f32_e32 v94, v94
	v_exp_f32_e32 v95, v95
	v_exp_f32_e32 v97, v97
	v_add_f32_e32 v192, 0, v190
	v_add_f32_e32 v193, 0, v191
	v_add_f32_e32 v98, v90, v98
	v_add_f32_e32 v99, v91, v99
	v_add_f32_e32 v192, v88, v192
	v_add_f32_e32 v193, v89, v193
	v_mfma_f32_32x32x16_bf16 v[20:35], v[136:139], v[84:87], v[20:35]
	v_cvt_pk_bf16_f32 v88, v90, v92
	v_cvt_pk_bf16_f32 v89, v91, v93
	v_cvt_pk_bf16_f32 v90, v94, v96
	v_cvt_pk_bf16_f32 v91, v95, v97
	v_add_f32_e64 v192, v92, v192
	v_add_f32_e64 v193, v93, v193
	v_add_f32_e32 v98, v94, v98
	v_add_f32_e32 v99, v95, v99
	v_add_f32_e32 v192, v96, v192
	v_add_f32_e32 v193, v97, v193
	v_mfma_f32_32x32x16_bf16 v[52:67], v[140:143], v[88:91], v[52:67]
	v_add_f32_e64 v98, v98, v192
	v_add_f32_e64 v99, v99, v193
	v_add_f32_e32 v98, v98, v99
	v_add_f32_e32 v187, v187, v98
	v_mfma_f32_32x32x16_bf16 v[20:35], v[132:135], v[88:91], v[20:35]
	s_branch .Lat_t1

.Lat_b2_nd:
	s_waitcnt lgkmcnt(0)
	v_cvt_f32_i32_e32 v189, s70
	v_fma_f32 v189, v167, v189, -v184
	s_nop 5
	v_add_f32_e32 v85, v189, v85
	v_add_f32_e32 v84, v189, v84
	v_exp_f32_e32 v190, v85
	v_add_f32_e32 v85, v189, v86
	v_add_f32_e32 v86, v189, v87
	v_add_f32_e32 v87, v189, v89
	v_exp_f32_e32 v84, v84
	v_exp_f32_e32 v85, v85
	v_exp_f32_e32 v191, v86
	v_add_f32_e32 v86, v189, v88
	v_exp_f32_e32 v88, v87
	v_add_f32_e32 v87, v189, v90
	v_add_f32_e32 v89, v189, v91
	v_exp_f32_e32 v86, v86
	v_exp_f32_e32 v87, v87
	v_exp_f32_e32 v89, v89
	v_add_f32_e32 v91, v189, v93
	v_add_f32_e32 v93, v189, v95
	v_add_f32_e32 v95, v189, v97
	v_add_f32_e32 v90, v189, v92
	v_exp_f32_e32 v92, v91
	v_add_f32_e32 v91, v189, v94
	v_add_f32_e32 v94, v189, v96
	v_exp_f32_e32 v96, v95
	v_add_f32_e32 v95, v189, v98
	v_add_f32_e32 v97, v189, v99
	v_add_f32_e32 v98, 0, v84
	v_add_f32_e32 v99, 0, v85
	v_cvt_pk_bf16_f32 v84, v84, v190
	v_add_f32_e32 v98, v86, v98
	v_add_f32_e32 v99, v87, v99
	v_cvt_pk_bf16_f32 v85, v85, v191
	v_cvt_pk_bf16_f32 v86, v86, v88
	v_cvt_pk_bf16_f32 v87, v87, v89
	v_exp_f32_e32 v90, v90
	v_exp_f32_e32 v91, v91
	v_mfma_f32_32x32x16_bf16 v[52:67], v[144:147], v[84:87], v[52:67]
	v_exp_f32_e32 v93, v93
	v_exp_f32_e32 v94, v94
	v_exp_f32_e32 v95, v95
	v_exp_f32_e32 v97, v97
	v_add_f32_e32 v192, 0, v190
	v_add_f32_e32 v193, 0, v191
	v_add_f32_e32 v98, v90, v98
	v_add_f32_e32 v99, v91, v99
	v_add_f32_e32 v192, v88, v192
	v_add_f32_e32 v193, v89, v193
	v_mfma_f32_32x32x16_bf16 v[20:35], v[136:139], v[84:87], v[20:35]
	v_cvt_pk_bf16_f32 v88, v90, v92
	v_cvt_pk_bf16_f32 v89, v91, v93
	v_cvt_pk_bf16_f32 v90, v94, v96
	v_cvt_pk_bf16_f32 v91, v95, v97
	v_add_f32_e64 v192, v92, v192
	v_add_f32_e64 v193, v93, v193
	v_add_f32_e32 v98, v94, v98
	v_add_f32_e32 v99, v95, v99
	v_add_f32_e32 v192, v96, v192
	v_add_f32_e32 v193, v97, v193
	v_mfma_f32_32x32x16_bf16 v[52:67], v[140:143], v[88:91], v[52:67]
	v_add_f32_e64 v98, v98, v192
	v_add_f32_e64 v99, v99, v193
	v_add_f32_e32 v98, v98, v99
	v_add_f32_e32 v187, v187, v98
	v_mfma_f32_32x32x16_bf16 v[20:35], v[132:135], v[88:91], v[20:35]
	v_mfma_f32_32x32x16_bf16 v[84:99], v[152:155], v[108:111], v[36:51]
	v_mfma_f32_32x32x16_bf16 v[84:99], v[148:151], v[112:115], v[84:99]
	ds_read_b128 v[152:155], v188 offset:4608
	ds_read_b128 v[148:151], v188 offset:4640
	ds_read2_b64 v[238:241], v2 offset0:8 offset1:10
	ds_read2_b64 v[242:245], v2 offset0:12 offset1:14
	ds_read2_b64 v[246:249], v233 offset0:40 offset1:42
	ds_read2_b64 v[210:213], v233 offset0:44 offset1:46
	s_cmp_lg_u32 s69, 0
	s_cbranch_scc1 .Lat_b2_nd1
	s_nop 4
	v_cndmask_b32_e64 v84, v84, v232, s[4:5]
	v_cndmask_b32_e64 v85, v232, v85, s[6:7]
	v_cndmask_b32_e64 v86, v86, v232, s[8:9]
	v_cndmask_b32_e64 v87, v87, v232, s[40:41]
	v_cndmask_b32_e64 v88, v88, v232, s[42:43]
	v_cndmask_b32_e64 v89, v89, v232, s[44:45]
	v_cndmask_b32_e64 v90, v90, v232, s[46:47]
	v_cndmask_b32_e64 v91, v91, v232, s[48:49]
	v_cndmask_b32_e64 v92, v92, v232, s[50:51]
	v_cndmask_b32_e64 v93, v93, v232, s[52:53]
	v_cndmask_b32_e64 v94, v94, v232, s[54:55]
	v_cndmask_b32_e64 v95, v95, v232, s[56:57]
	v_cndmask_b32_e64 v96, v96, v232, s[58:59]
	v_cndmask_b32_e64 v97, v97, v232, s[60:61]
	v_cndmask_b32_e64 v98, v98, v232, s[62:63]
	v_cndmask_b32_e64 v99, v99, v232, s[64:65]
.Lat_b2_nd1:
	v_cvt_f32_i32_e32 v234, s69
	v_fma_f32 v236, v167, v234, -v177
	s_nop 2
	v_add_f32_e32 v85, v236, v85
	v_add_f32_e32 v84, v236, v84
	v_exp_f32_e32 v234, v85
	v_add_f32_e32 v85, v236, v86
	v_add_f32_e32 v86, v236, v87
	v_add_f32_e32 v87, v236, v89
	v_exp_f32_e32 v84, v84
	v_exp_f32_e32 v85, v85
	v_exp_f32_e32 v235, v86
	v_add_f32_e32 v86, v236, v88
	v_exp_f32_e32 v88, v87
	v_add_f32_e32 v87, v236, v90
	v_add_f32_e32 v89, v236, v91
	v_exp_f32_e32 v86, v86
	v_exp_f32_e32 v87, v87
	v_exp_f32_e32 v89, v89
	v_add_f32_e32 v91, v236, v93
	v_add_f32_e32 v93, v236, v95
	v_add_f32_e32 v95, v236, v97
	v_add_f32_e32 v90, v236, v92
	v_exp_f32_e32 v92, v91
	v_add_f32_e32 v91, v236, v94
	v_add_f32_e32 v94, v236, v96
	v_exp_f32_e32 v96, v95
	v_add_f32_e32 v95, v236, v98
	v_add_f32_e32 v97, v236, v99
	v_add_f32_e32 v98, 0, v84
	v_add_f32_e32 v99, 0, v85
	v_cvt_pk_bf16_f32 v84, v84, v234
	v_add_f32_e32 v98, v86, v98
	v_add_f32_e32 v99, v87, v99
	v_cvt_pk_bf16_f32 v85, v85, v235
	v_cvt_pk_bf16_f32 v86, v86, v88
	v_cvt_pk_bf16_f32 v87, v87, v89
	v_exp_f32_e32 v90, v90
	v_exp_f32_e32 v91, v91
	v_mfma_f32_32x32x16_bf16 v[68:83], v[144:147], v[84:87], v[68:83]
	v_exp_f32_e32 v93, v93
	v_exp_f32_e32 v94, v94
	v_exp_f32_e32 v95, v95
	v_exp_f32_e32 v97, v97
	v_add_f32_e32 v236, 0, v234
	v_add_f32_e32 v237, 0, v235
	v_add_f32_e32 v98, v90, v98
	v_add_f32_e32 v99, v91, v99
	v_add_f32_e32 v236, v88, v236
	v_add_f32_e32 v237, v89, v237
	v_mfma_f32_32x32x16_bf16 v[4:19], v[136:139], v[84:87], v[4:19]
	v_cvt_pk_bf16_f32 v88, v90, v92
	v_cvt_pk_bf16_f32 v89, v91, v93
	v_cvt_pk_bf16_f32 v90, v94, v96
	v_cvt_pk_bf16_f32 v91, v95, v97
	v_add_f32_e64 v236, v92, v236
	v_add_f32_e64 v237, v93, v237
	v_add_f32_e32 v98, v94, v98
	v_add_f32_e32 v99, v95, v99
	v_add_f32_e32 v236, v96, v236
	v_add_f32_e32 v237, v97, v237
	v_mfma_f32_32x32x16_bf16 v[68:83], v[140:143], v[88:91], v[68:83]
	v_add_f32_e64 v98, v98, v236
	v_add_f32_e64 v99, v99, v237
	v_add_f32_e32 v98, v98, v99
	v_add_f32_e32 v183, v183, v98
	v_mfma_f32_32x32x16_bf16 v[4:19], v[132:135], v[88:91], v[4:19]
.Lat_t1:
	s_sub_i32 s71, s67, 2
	s_sub_i32 s70, s68, 2
	s_sub_i32 s69, s31, 2
	s_waitcnt lgkmcnt(4)
	v_mfma_f32_32x32x16_bf16 v[84:99], v[152:155], v[100:103], v[36:51]
	v_mfma_f32_32x32x16_bf16 v[84:99], v[148:151], v[104:107], v[84:99]
	s_cmp_le_u32 s71, s15
	s_cbranch_scc1 .Lat_b1
	ds_read_b128 v[152:155], v188
	ds_read_b128 v[148:151], v188 offset:32
	ds_read2_b64 v[144:147], v2 offset0:0 offset1:2
	ds_read2_b64 v[140:143], v2 offset0:4 offset1:6
	ds_read2_b64 v[136:139], v233 offset0:32 offset1:34
	ds_read2_b64 v[132:135], v233 offset0:36 offset1:38
	s_cmp_lg_u32 s70, 0
	s_cbranch_scc1 .Lat_o1_nd
	s_nop 2
	v_cndmask_b32_e64 v84, v84, v232, s[4:5]
	v_cndmask_b32_e64 v85, v232, v85, s[6:7]
	v_cndmask_b32_e64 v86, v86, v232, s[8:9]
	v_cndmask_b32_e64 v87, v87, v232, s[40:41]
	v_cndmask_b32_e64 v88, v88, v232, s[42:43]
	v_cndmask_b32_e64 v89, v89, v232, s[44:45]
	v_cndmask_b32_e64 v90, v90, v232, s[46:47]
	v_cndmask_b32_e64 v91, v91, v232, s[48:49]
	v_cndmask_b32_e64 v92, v92, v232, s[50:51]
	v_cndmask_b32_e64 v93, v93, v232, s[52:53]
	v_cndmask_b32_e64 v94, v94, v232, s[54:55]
	v_cndmask_b32_e64 v95, v95, v232, s[56:57]
	v_cndmask_b32_e64 v96, v96, v232, s[58:59]
	v_cndmask_b32_e64 v97, v97, v232, s[60:61]
	v_cndmask_b32_e64 v98, v98, v232, s[62:63]
	v_cndmask_b32_e64 v99, v99, v232, s[64:65]

.Lat_b1_nd:
	s_waitcnt lgkmcnt(0)
	v_cvt_f32_i32_e32 v189, s70
	v_fma_f32 v189, v167, v189, -v184
	s_nop 5
	v_add_f32_e32 v85, v189, v85
	v_add_f32_e32 v84, v189, v84
	v_exp_f32_e32 v190, v85
	v_add_f32_e32 v85, v189, v86
	v_add_f32_e32 v86, v189, v87
	v_add_f32_e32 v87, v189, v89
	v_exp_f32_e32 v84, v84
	v_exp_f32_e32 v85, v85
	v_exp_f32_e32 v191, v86
	v_add_f32_e32 v86, v189, v88
	v_exp_f32_e32 v88, v87
	v_add_f32_e32 v87, v189, v90
	v_add_f32_e32 v89, v189, v91
	v_exp_f32_e32 v86, v86
	v_exp_f32_e32 v87, v87
	v_exp_f32_e32 v89, v89
	v_add_f32_e32 v91, v189, v93
	v_add_f32_e32 v93, v189, v95
	v_add_f32_e32 v95, v189, v97
	v_add_f32_e32 v90, v189, v92
	v_exp_f32_e32 v92, v91
	v_add_f32_e32 v91, v189, v94
	v_add_f32_e32 v94, v189, v96
	v_exp_f32_e32 v96, v95
	v_add_f32_e32 v95, v189, v98
	v_add_f32_e32 v97, v189, v99
	v_add_f32_e32 v98, 0, v84
	v_add_f32_e32 v99, 0, v85
	v_cvt_pk_bf16_f32 v84, v84, v190
	v_add_f32_e32 v98, v86, v98
	v_add_f32_e32 v99, v87, v99
	v_cvt_pk_bf16_f32 v85, v85, v191
	v_cvt_pk_bf16_f32 v86, v86, v88
	v_cvt_pk_bf16_f32 v87, v87, v89
	v_exp_f32_e32 v90, v90
	v_exp_f32_e32 v91, v91
	v_mfma_f32_32x32x16_bf16 v[52:67], v[238:241], v[84:87], v[52:67]
	v_exp_f32_e32 v93, v93
	v_exp_f32_e32 v94, v94
	v_exp_f32_e32 v95, v95
	v_exp_f32_e32 v97, v97
	v_add_f32_e32 v192, 0, v190
	v_add_f32_e32 v193, 0, v191
	v_add_f32_e32 v98, v90, v98
	v_add_f32_e32 v99, v91, v99
	v_add_f32_e32 v192, v88, v192
	v_add_f32_e32 v193, v89, v193
	v_mfma_f32_32x32x16_bf16 v[20:35], v[246:249], v[84:87], v[20:35]
	v_cvt_pk_bf16_f32 v88, v90, v92
	v_cvt_pk_bf16_f32 v89, v91, v93
	v_cvt_pk_bf16_f32 v90, v94, v96
	v_cvt_pk_bf16_f32 v91, v95, v97
	v_add_f32_e64 v192, v92, v192
	v_add_f32_e64 v193, v93, v193
	v_add_f32_e32 v98, v94, v98
	v_add_f32_e32 v99, v95, v99
	v_add_f32_e32 v192, v96, v192
	v_add_f32_e32 v193, v97, v193
	v_mfma_f32_32x32x16_bf16 v[52:67], v[242:245], v[88:91], v[52:67]
	v_add_f32_e64 v98, v98, v192
	v_add_f32_e64 v99, v99, v193
	v_add_f32_e32 v98, v98, v99
	v_add_f32_e32 v187, v187, v98
	v_mfma_f32_32x32x16_bf16 v[20:35], v[210:213], v[88:91], v[20:35]
	v_mfma_f32_32x32x16_bf16 v[84:99], v[152:155], v[108:111], v[36:51]
	v_mfma_f32_32x32x16_bf16 v[84:99], v[148:151], v[112:115], v[84:99]
	ds_read_b128 v[152:155], v188
	ds_read_b128 v[148:151], v188 offset:32
	ds_read2_b64 v[144:147], v2 offset0:0 offset1:2
	ds_read2_b64 v[140:143], v2 offset0:4 offset1:6
	ds_read2_b64 v[136:139], v233 offset0:32 offset1:34
	ds_read2_b64 v[132:135], v233 offset0:36 offset1:38
	s_cmp_lg_u32 s69, 0
	s_cbranch_scc1 .Lat_b1_nd1
	s_nop 4
	v_cndmask_b32_e64 v84, v84, v232, s[4:5]
	v_cndmask_b32_e64 v85, v232, v85, s[6:7]
	v_cndmask_b32_e64 v86, v86, v232, s[8:9]
	v_cndmask_b32_e64 v87, v87, v232, s[40:41]
	v_cndmask_b32_e64 v88, v88, v232, s[42:43]
	v_cndmask_b32_e64 v89, v89, v232, s[44:45]
	v_cndmask_b32_e64 v90, v90, v232, s[46:47]
	v_cndmask_b32_e64 v91, v91, v232, s[48:49]
	v_cndmask_b32_e64 v92, v92, v232, s[50:51]
	v_cndmask_b32_e64 v93, v93, v232, s[52:53]
	v_cndmask_b32_e64 v94, v94, v232, s[54:55]
	v_cndmask_b32_e64 v95, v95, v232, s[56:57]
	v_cndmask_b32_e64 v96, v96, v232, s[58:59]
	v_cndmask_b32_e64 v97, v97, v232, s[60:61]
	v_cndmask_b32_e64 v98, v98, v232, s[62:63]
	v_cndmask_b32_e64 v99, v99, v232, s[64:65]

.Lat_t0:
	s_sub_i32 s71, s67, 3
	s_sub_i32 s70, s68, 3
	s_sub_i32 s69, s31, 3
	s_waitcnt lgkmcnt(4)
	v_mfma_f32_32x32x16_bf16 v[84:99], v[152:155], v[100:103], v[36:51]
	v_mfma_f32_32x32x16_bf16 v[84:99], v[148:151], v[104:107], v[84:99]
	s_cmp_le_u32 s71, s15
	s_cbranch_scc1 .Lat_b0
	s_cmp_lg_u32 s70, 0
	s_cbranch_scc1 .Lat_o0_nd
	s_nop 8
	v_cndmask_b32_e64 v84, v84, v232, s[4:5]
	v_cndmask_b32_e64 v85, v232, v85, s[6:7]
	v_cndmask_b32_e64 v86, v86, v232, s[8:9]
	v_cndmask_b32_e64 v87, v87, v232, s[40:41]
	v_cndmask_b32_e64 v88, v88, v232, s[42:43]
	v_cndmask_b32_e64 v89, v89, v232, s[44:45]
	v_cndmask_b32_e64 v90, v90, v232, s[46:47]
	v_cndmask_b32_e64 v91, v91, v232, s[48:49]
	v_cndmask_b32_e64 v92, v92, v232, s[50:51]
	v_cndmask_b32_e64 v93, v93, v232, s[52:53]
	v_cndmask_b32_e64 v94, v94, v232, s[54:55]
	v_cndmask_b32_e64 v95, v95, v232, s[56:57]
	v_cndmask_b32_e64 v96, v96, v232, s[58:59]
	v_cndmask_b32_e64 v97, v97, v232, s[60:61]
	v_cndmask_b32_e64 v98, v98, v232, s[62:63]
	v_cndmask_b32_e64 v99, v99, v232, s[64:65]
.Lat_o0_nd:
	s_waitcnt lgkmcnt(0)
	v_cvt_f32_i32_e32 v189, s70
	v_fma_f32 v189, v167, v189, -v184
	s_nop 5
	v_add_f32_e32 v85, v189, v85
	v_add_f32_e32 v84, v189, v84
	v_exp_f32_e32 v190, v85
	v_add_f32_e32 v85, v189, v86
	v_add_f32_e32 v86, v189, v87
	v_add_f32_e32 v87, v189, v89
	v_exp_f32_e32 v84, v84
	v_exp_f32_e32 v85, v85
	v_exp_f32_e32 v191, v86
	v_add_f32_e32 v86, v189, v88
	v_exp_f32_e32 v88, v87
	v_add_f32_e32 v87, v189, v90
	v_add_f32_e32 v89, v189, v91
	v_exp_f32_e32 v86, v86
	v_exp_f32_e32 v87, v87
	v_exp_f32_e32 v89, v89
	v_add_f32_e32 v91, v189, v93
	v_add_f32_e32 v93, v189, v95
	v_add_f32_e32 v95, v189, v97
	v_add_f32_e32 v90, v189, v92
	v_exp_f32_e32 v92, v91
	v_add_f32_e32 v91, v189, v94
	v_add_f32_e32 v94, v189, v96
	v_exp_f32_e32 v96, v95
	v_add_f32_e32 v95, v189, v98
	v_add_f32_e32 v97, v189, v99
	v_add_f32_e32 v98, 0, v84
	v_add_f32_e32 v99, 0, v85
	v_cvt_pk_bf16_f32 v84, v84, v190
	v_add_f32_e32 v98, v86, v98
	v_add_f32_e32 v99, v87, v99
	v_cvt_pk_bf16_f32 v85, v85, v191
	v_cvt_pk_bf16_f32 v86, v86, v88
	v_cvt_pk_bf16_f32 v87, v87, v89
	v_exp_f32_e32 v90, v90
	v_exp_f32_e32 v91, v91
	v_mfma_f32_32x32x16_bf16 v[52:67], v[144:147], v[84:87], v[52:67]
	v_exp_f32_e32 v93, v93
	v_exp_f32_e32 v94, v94
	v_exp_f32_e32 v95, v95
	v_exp_f32_e32 v97, v97
	v_add_f32_e32 v192, 0, v190
	v_add_f32_e32 v193, 0, v191
	v_add_f32_e32 v98, v90, v98
	v_add_f32_e32 v99, v91, v99
	v_add_f32_e32 v192, v88, v192
	v_add_f32_e32 v193, v89, v193
	v_mfma_f32_32x32x16_bf16 v[20:35], v[136:139], v[84:87], v[20:35]
	v_cvt_pk_bf16_f32 v88, v90, v92
	v_cvt_pk_bf16_f32 v89, v91, v93
	v_cvt_pk_bf16_f32 v90, v94, v96
	v_cvt_pk_bf16_f32 v91, v95, v97
	v_add_f32_e64 v192, v92, v192
	v_add_f32_e64 v193, v93, v193
	v_add_f32_e32 v98, v94, v98
	v_add_f32_e32 v99, v95, v99
	v_add_f32_e32 v192, v96, v192
	v_add_f32_e32 v193, v97, v193
	v_mfma_f32_32x32x16_bf16 v[52:67], v[140:143], v[88:91], v[52:67]
	v_add_f32_e64 v98, v98, v192
	v_add_f32_e64 v99, v99, v193
	v_add_f32_e32 v98, v98, v99
	v_add_f32_e32 v187, v187, v98
	v_mfma_f32_32x32x16_bf16 v[20:35], v[132:135], v[88:91], v[20:35]
	s_branch .LBB0_696

.Lat_b0_nd:
	s_waitcnt lgkmcnt(0)
	v_cvt_f32_i32_e32 v189, s70
	v_fma_f32 v189, v167, v189, -v184
	s_nop 5
	v_add_f32_e32 v85, v189, v85
	v_add_f32_e32 v84, v189, v84
	v_exp_f32_e32 v190, v85
	v_add_f32_e32 v85, v189, v86
	v_add_f32_e32 v86, v189, v87
	v_add_f32_e32 v87, v189, v89
	v_exp_f32_e32 v84, v84
	v_exp_f32_e32 v85, v85
	v_exp_f32_e32 v191, v86
	v_add_f32_e32 v86, v189, v88
	v_exp_f32_e32 v88, v87
	v_add_f32_e32 v87, v189, v90
	v_add_f32_e32 v89, v189, v91
	v_exp_f32_e32 v86, v86
	v_exp_f32_e32 v87, v87
	v_exp_f32_e32 v89, v89
	v_add_f32_e32 v91, v189, v93
	v_add_f32_e32 v93, v189, v95
	v_add_f32_e32 v95, v189, v97
	v_add_f32_e32 v90, v189, v92
	v_exp_f32_e32 v92, v91
	v_add_f32_e32 v91, v189, v94
	v_add_f32_e32 v94, v189, v96
	v_exp_f32_e32 v96, v95
	v_add_f32_e32 v95, v189, v98
	v_add_f32_e32 v97, v189, v99
	v_add_f32_e32 v98, 0, v84
	v_add_f32_e32 v99, 0, v85
	v_cvt_pk_bf16_f32 v84, v84, v190
	v_add_f32_e32 v98, v86, v98
	v_add_f32_e32 v99, v87, v99
	v_cvt_pk_bf16_f32 v85, v85, v191
	v_cvt_pk_bf16_f32 v86, v86, v88
	v_cvt_pk_bf16_f32 v87, v87, v89
	v_exp_f32_e32 v90, v90
	v_exp_f32_e32 v91, v91
	v_mfma_f32_32x32x16_bf16 v[52:67], v[144:147], v[84:87], v[52:67]
	v_exp_f32_e32 v93, v93
	v_exp_f32_e32 v94, v94
	v_exp_f32_e32 v95, v95
	v_exp_f32_e32 v97, v97
	v_add_f32_e32 v192, 0, v190
	v_add_f32_e32 v193, 0, v191
	v_add_f32_e32 v98, v90, v98
	v_add_f32_e32 v99, v91, v99
	v_add_f32_e32 v192, v88, v192
	v_add_f32_e32 v193, v89, v193
	v_mfma_f32_32x32x16_bf16 v[20:35], v[136:139], v[84:87], v[20:35]
	v_cvt_pk_bf16_f32 v88, v90, v92
	v_cvt_pk_bf16_f32 v89, v91, v93
	v_cvt_pk_bf16_f32 v90, v94, v96
	v_cvt_pk_bf16_f32 v91, v95, v97
	v_add_f32_e64 v192, v92, v192
	v_add_f32_e64 v193, v93, v193
	v_add_f32_e32 v98, v94, v98
	v_add_f32_e32 v99, v95, v99
	v_add_f32_e32 v192, v96, v192
	v_add_f32_e32 v193, v97, v193
	v_mfma_f32_32x32x16_bf16 v[52:67], v[140:143], v[88:91], v[52:67]
	v_add_f32_e64 v98, v98, v192
	v_add_f32_e64 v99, v99, v193
	v_add_f32_e32 v98, v98, v99
	v_add_f32_e32 v187, v187, v98
	v_mfma_f32_32x32x16_bf16 v[20:35], v[132:135], v[88:91], v[20:35]
	v_mfma_f32_32x32x16_bf16 v[84:99], v[152:155], v[108:111], v[36:51]
	v_mfma_f32_32x32x16_bf16 v[84:99], v[148:151], v[112:115], v[84:99]
	s_cmp_lg_u32 s69, 0
	s_cbranch_scc1 .Lat_b0_nd1
	s_nop 10
	v_cndmask_b32_e64 v84, v84, v232, s[4:5]
	v_cndmask_b32_e64 v85, v232, v85, s[6:7]
	v_cndmask_b32_e64 v86, v86, v232, s[8:9]
	v_cndmask_b32_e64 v87, v87, v232, s[40:41]
	v_cndmask_b32_e64 v88, v88, v232, s[42:43]
	v_cndmask_b32_e64 v89, v89, v232, s[44:45]
	v_cndmask_b32_e64 v90, v90, v232, s[46:47]
	v_cndmask_b32_e64 v91, v91, v232, s[48:49]
	v_cndmask_b32_e64 v92, v92, v232, s[50:51]
	v_cndmask_b32_e64 v93, v93, v232, s[52:53]
	v_cndmask_b32_e64 v94, v94, v232, s[54:55]
	v_cndmask_b32_e64 v95, v95, v232, s[56:57]
	v_cndmask_b32_e64 v96, v96, v232, s[58:59]
	v_cndmask_b32_e64 v97, v97, v232, s[60:61]
	v_cndmask_b32_e64 v98, v98, v232, s[62:63]
	v_cndmask_b32_e64 v99, v99, v232, s[64:65]
.Lat_b0_nd1:
	v_cvt_f32_i32_e32 v234, s69
	v_fma_f32 v236, v167, v234, -v177
	s_nop 8
	v_add_f32_e32 v85, v236, v85
	v_add_f32_e32 v84, v236, v84
	v_exp_f32_e32 v234, v85
	v_add_f32_e32 v85, v236, v86
	v_add_f32_e32 v86, v236, v87
	v_add_f32_e32 v87, v236, v89
	v_exp_f32_e32 v84, v84
	v_exp_f32_e32 v85, v85
	v_exp_f32_e32 v235, v86
	v_add_f32_e32 v86, v236, v88
	v_exp_f32_e32 v88, v87
	v_add_f32_e32 v87, v236, v90
	v_add_f32_e32 v89, v236, v91
	v_exp_f32_e32 v86, v86
	v_exp_f32_e32 v87, v87
	v_exp_f32_e32 v89, v89
	v_add_f32_e32 v91, v236, v93
	v_add_f32_e32 v93, v236, v95
	v_add_f32_e32 v95, v236, v97
	v_add_f32_e32 v90, v236, v92
	v_exp_f32_e32 v92, v91
	v_add_f32_e32 v91, v236, v94
	v_add_f32_e32 v94, v236, v96
	v_exp_f32_e32 v96, v95
	v_add_f32_e32 v95, v236, v98
	v_add_f32_e32 v97, v236, v99
	v_add_f32_e32 v98, 0, v84
	v_add_f32_e32 v99, 0, v85
	v_cvt_pk_bf16_f32 v84, v84, v234
	v_add_f32_e32 v98, v86, v98
	v_add_f32_e32 v99, v87, v99
	v_cvt_pk_bf16_f32 v85, v85, v235
	v_cvt_pk_bf16_f32 v86, v86, v88
	v_cvt_pk_bf16_f32 v87, v87, v89
	v_exp_f32_e32 v90, v90
	v_exp_f32_e32 v91, v91
	v_mfma_f32_32x32x16_bf16 v[68:83], v[144:147], v[84:87], v[68:83]
	v_exp_f32_e32 v93, v93
	v_exp_f32_e32 v94, v94
	v_exp_f32_e32 v95, v95
	v_exp_f32_e32 v97, v97
	v_add_f32_e32 v236, 0, v234
	v_add_f32_e32 v237, 0, v235
	v_add_f32_e32 v98, v90, v98
	v_add_f32_e32 v99, v91, v99
	v_add_f32_e32 v236, v88, v236
	v_add_f32_e32 v237, v89, v237
	v_mfma_f32_32x32x16_bf16 v[4:19], v[136:139], v[84:87], v[4:19]
	v_cvt_pk_bf16_f32 v88, v90, v92
	v_cvt_pk_bf16_f32 v89, v91, v93
	v_cvt_pk_bf16_f32 v90, v94, v96
	v_cvt_pk_bf16_f32 v91, v95, v97
	v_add_f32_e64 v236, v92, v236
	v_add_f32_e64 v237, v93, v237
	v_add_f32_e32 v98, v94, v98
	v_add_f32_e32 v99, v95, v99
	v_add_f32_e32 v236, v96, v236
	v_add_f32_e32 v237, v97, v237
	v_mfma_f32_32x32x16_bf16 v[68:83], v[140:143], v[88:91], v[68:83]
	v_add_f32_e64 v98, v98, v236
	v_add_f32_e64 v99, v99, v237
	v_add_f32_e32 v98, v98, v99
	v_add_f32_e32 v183, v183, v98
	v_mfma_f32_32x32x16_bf16 v[4:19], v[132:135], v[88:91], v[4:19]

.LBB0_700:
	v_mul_f32_e32 v2, 0x3fb8aa3b, v161
	v_exp_f32_e32 v2, v2
	v_mov_b32_e32 v36, v187
	v_mov_b32_e32 v37, v183
	v_readlane_b32 s4, v254, 60
	v_sub_f32_e32 v2, v165, v2
	v_permlane32_swap_b32_e32 v187, v36
	v_permlane32_swap_b32_e32 v183, v37
	v_add_f32_e32 v2, s4, v2
	v_add_f32_e32 v36, v187, v36
	v_add_f32_e32 v37, v183, v37
	v_cndmask_b32_e64 v2, v2, 1.0, s[38:39]
	v_cndmask_b32_e64 v38, v36, v37, s[38:39]
	v_div_scale_f32 v39, s[4:5], v38, v38, v2
	v_rcp_f32_e32 v40, v39
	v_readlane_b32 s4, v254, 1
	v_cndmask_b32_e64 v44, v64, v80, s[38:39]
	v_cndmask_b32_e64 v45, v63, v79, s[38:39]
	v_fma_f32 v41, -v39, v40, 1.0
	v_fmac_f32_e32 v40, v41, v40
	v_div_scale_f32 v41, vcc, v2, v38, v2
	v_mul_f32_e32 v42, v41, v40
	v_fma_f32 v43, -v39, v42, v41
	v_fmac_f32_e32 v42, v43, v40
	v_fma_f32 v39, -v39, v42, v41
	v_div_fmas_f32 v39, v39, v40, v42
	v_div_fixup_f32 v38, v39, v38, v2
	v_lshlrev_b32_e32 v39, 2, v163
	v_cndmask_b32_e64 v41, v67, v83, s[38:39]
	v_cndmask_b32_e64 v42, v66, v82, s[38:39]
	v_add_u32_e32 v40, s4, v39
	v_mul_f32_e32 v42, v42, v38
	v_mul_f32_e32 v41, v41, v38
	v_cndmask_b32_e64 v43, v65, v81, s[38:39]
	v_cndmask_b32_e64 v46, v62, v78, s[38:39]
	v_cndmask_b32_e64 v47, v61, v77, s[38:39]
	v_cndmask_b32_e64 v48, v60, v76, s[38:39]
	v_cndmask_b32_e64 v49, v59, v75, s[38:39]
	v_cndmask_b32_e64 v50, v58, v74, s[38:39]
	v_cndmask_b32_e64 v51, v57, v73, s[38:39]
	v_cndmask_b32_e64 v84, v56, v72, s[38:39]
	v_cndmask_b32_e64 v85, v55, v71, s[38:39]
	v_cndmask_b32_e64 v86, v54, v70, s[38:39]
	v_cndmask_b32_e64 v87, v53, v69, s[38:39]
	v_cndmask_b32_e64 v88, v52, v68, s[38:39]
	ds_write2st64_b32 v40, v42, v41 offset0:14 offset1:15
	v_cndmask_b32_e64 v41, v35, v19, s[38:39]
	v_cndmask_b32_e64 v42, v34, v18, s[38:39]
	v_mul_f32_e32 v88, v88, v38
	v_mul_f32_e32 v87, v87, v38
	v_mul_f32_e32 v86, v86, v38
	v_mul_f32_e32 v85, v85, v38
	v_mul_f32_e32 v84, v84, v38
	v_mul_f32_e32 v51, v51, v38
	v_mul_f32_e32 v50, v50, v38
	v_mul_f32_e32 v49, v49, v38
	v_mul_f32_e32 v48, v48, v38
	v_mul_f32_e32 v47, v47, v38
	v_mul_f32_e32 v46, v46, v38
	v_mul_f32_e32 v45, v45, v38
	v_mul_f32_e32 v44, v44, v38
	v_mul_f32_e32 v43, v43, v38
	v_mul_f32_e32 v42, v42, v38
	v_cndmask_b32_e64 v36, v37, v36, s[38:39]
	v_mul_f32_e32 v37, v41, v38
	ds_write2st64_b32 v40, v88, v87 offset1:1
	ds_write2st64_b32 v40, v86, v85 offset0:2 offset1:3
	ds_write2st64_b32 v40, v84, v51 offset0:4 offset1:5
	ds_write2st64_b32 v40, v50, v49 offset0:6 offset1:7
	ds_write2st64_b32 v40, v48, v47 offset0:8 offset1:9
	ds_write2st64_b32 v40, v46, v45 offset0:10 offset1:11
	ds_write2st64_b32 v40, v44, v43 offset0:12 offset1:13
	v_cndmask_b32_e64 v43, v33, v17, s[38:39]
	v_cndmask_b32_e64 v44, v32, v16, s[38:39]
	v_cndmask_b32_e64 v45, v31, v15, s[38:39]
	v_cndmask_b32_e64 v46, v30, v14, s[38:39]
	v_cndmask_b32_e64 v47, v29, v13, s[38:39]
	v_cndmask_b32_e64 v48, v28, v12, s[38:39]
	v_cndmask_b32_e64 v49, v27, v11, s[38:39]
	v_cndmask_b32_e64 v50, v26, v10, s[38:39]
	v_cndmask_b32_e64 v51, v25, v9, s[38:39]
	v_cndmask_b32_e64 v84, v24, v8, s[38:39]
	v_cndmask_b32_e64 v85, v23, v7, s[38:39]
	v_cndmask_b32_e64 v86, v22, v6, s[38:39]
	v_cndmask_b32_e64 v87, v21, v5, s[38:39]
	v_cndmask_b32_e64 v88, v20, v4, s[38:39]
	ds_write2st64_b32 v40, v42, v37 offset0:30 offset1:31
	v_div_scale_f32 v37, s[4:5], v36, v36, v2
	v_mul_f32_e32 v88, v88, v38
	v_mul_f32_e32 v87, v87, v38
	v_mul_f32_e32 v86, v86, v38
	v_mul_f32_e32 v85, v85, v38
	v_mul_f32_e32 v84, v84, v38
	v_mul_f32_e32 v51, v51, v38
	v_mul_f32_e32 v50, v50, v38
	v_mul_f32_e32 v49, v49, v38
	v_mul_f32_e32 v48, v48, v38
	v_mul_f32_e32 v47, v47, v38
	v_mul_f32_e32 v46, v46, v38
	v_mul_f32_e32 v45, v45, v38
	v_mul_f32_e32 v44, v44, v38
	v_mul_f32_e32 v43, v43, v38
	v_rcp_f32_e32 v38, v37
	ds_write2st64_b32 v40, v88, v87 offset0:16 offset1:17
	ds_write2st64_b32 v40, v86, v85 offset0:18 offset1:19
	ds_write2st64_b32 v40, v84, v51 offset0:20 offset1:21
	ds_write2st64_b32 v40, v50, v49 offset0:22 offset1:23
	ds_write2st64_b32 v40, v48, v47 offset0:24 offset1:25
	ds_write2st64_b32 v40, v46, v45 offset0:26 offset1:27
	ds_write2st64_b32 v40, v44, v43 offset0:28 offset1:29
	v_fma_f32 v40, -v37, v38, 1.0
	v_fmac_f32_e32 v38, v40, v38
	v_div_scale_f32 v40, vcc, v2, v36, v2
	v_readlane_b32 s4, v254, 2
	v_mul_f32_e32 v41, v40, v38
	s_waitcnt lgkmcnt(0)
	v_add_u32_e32 v84, s4, v39
	s_barrier
	v_fma_f32 v42, -v37, v41, v40
	v_cndmask_b32_e64 v51, v69, v53, s[38:39]
	v_cndmask_b32_e64 v50, v68, v52, s[38:39]
	ds_read2st64_b32 v[52:53], v84 offset1:1
	v_fmac_f32_e32 v41, v42, v38
	v_fma_f32 v37, -v37, v41, v40
	v_div_fmas_f32 v37, v37, v38, v41
	v_div_fixup_f32 v2, v37, v36, v2
	v_cndmask_b32_e64 v43, v77, v61, s[38:39]
	v_cndmask_b32_e64 v42, v76, v60, s[38:39]
	s_waitcnt lgkmcnt(0)
	v_pk_fma_f32 v[60:61], v[50:51], v[2:3], v[52:53] op_sel_hi:[1,0,1] neg_lo:[0,0,1] neg_hi:[0,0,1]
	ds_read2st64_b32 v[50:51], v84 offset0:2 offset1:3
	v_cndmask_b32_e64 v49, v71, v55, s[38:39]
	v_cndmask_b32_e64 v48, v70, v54, s[38:39]
	v_cndmask_b32_e64 v39, v81, v65, s[38:39]
	v_cndmask_b32_e64 v38, v80, v64, s[38:39]
	s_waitcnt lgkmcnt(0)
	v_pk_fma_f32 v[64:65], v[48:49], v[2:3], v[50:51] op_sel_hi:[1,0,1] neg_lo:[0,0,1] neg_hi:[0,0,1]
	ds_read2st64_b32 v[48:49], v84 offset0:4 offset1:5
	v_cndmask_b32_e64 v47, v73, v57, s[38:39]
	v_cndmask_b32_e64 v46, v72, v56, s[38:39]
	v_cndmask_b32_e64 v41, v79, v63, s[38:39]
	v_cndmask_b32_e64 v40, v78, v62, s[38:39]
	s_waitcnt lgkmcnt(0)
	v_pk_fma_f32 v[62:63], v[46:47], v[2:3], v[48:49] op_sel_hi:[1,0,1] neg_lo:[0,0,1] neg_hi:[0,0,1]
	ds_read2st64_b32 v[46:47], v84 offset0:6 offset1:7
	v_cndmask_b32_e64 v45, v75, v59, s[38:39]
	v_cndmask_b32_e64 v44, v74, v58, s[38:39]
	v_cndmask_b32_e64 v37, v83, v67, s[38:39]
	v_cndmask_b32_e64 v36, v82, v66, s[38:39]
	s_waitcnt lgkmcnt(0)
	v_pk_fma_f32 v[66:67], v[44:45], v[2:3], v[46:47] op_sel_hi:[1,0,1] neg_lo:[0,0,1] neg_hi:[0,0,1]
	ds_read2st64_b32 v[44:45], v84 offset0:8 offset1:9
	v_cndmask_b32_e64 v5, v5, v21, s[38:39]
	v_cndmask_b32_e64 v4, v4, v20, s[38:39]
	v_cndmask_b32_e64 v7, v7, v23, s[38:39]
	v_cndmask_b32_e64 v6, v6, v22, s[38:39]
	s_waitcnt lgkmcnt(0)
	v_pk_fma_f32 v[56:57], v[42:43], v[2:3], v[44:45] op_sel_hi:[1,0,1] neg_lo:[0,0,1] neg_hi:[0,0,1]
	ds_read2st64_b32 v[42:43], v84 offset0:10 offset1:11
	v_cndmask_b32_e64 v9, v9, v25, s[38:39]
	v_cndmask_b32_e64 v8, v8, v24, s[38:39]
	v_cndmask_b32_e64 v11, v11, v27, s[38:39]
	v_cndmask_b32_e64 v10, v10, v26, s[38:39]
	s_waitcnt lgkmcnt(0)
	v_pk_fma_f32 v[58:59], v[40:41], v[2:3], v[42:43] op_sel_hi:[1,0,1] neg_lo:[0,0,1] neg_hi:[0,0,1]
	ds_read2st64_b32 v[40:41], v84 offset0:12 offset1:13
	v_cndmask_b32_e64 v13, v13, v29, s[38:39]
	v_cndmask_b32_e64 v12, v12, v28, s[38:39]
	v_cndmask_b32_e64 v15, v15, v31, s[38:39]
	v_cndmask_b32_e64 v14, v14, v30, s[38:39]
	s_waitcnt lgkmcnt(0)
	v_pk_fma_f32 v[46:47], v[38:39], v[2:3], v[40:41] op_sel_hi:[1,0,1] neg_lo:[0,0,1] neg_hi:[0,0,1]
	ds_read2st64_b32 v[38:39], v84 offset0:14 offset1:15
	v_cndmask_b32_e64 v17, v17, v33, s[38:39]
	v_cndmask_b32_e64 v16, v16, v32, s[38:39]
	v_readlane_b32 s4, v253, 63
	v_cndmask_b32_e64 v18, v18, v34, s[38:39]
	s_waitcnt lgkmcnt(0)
	v_pk_fma_f32 v[54:55], v[36:37], v[2:3], v[38:39] op_sel_hi:[1,0,1] neg_lo:[0,0,1] neg_hi:[0,0,1]
	ds_read2st64_b32 v[36:37], v84 offset0:16 offset1:17
	v_readlane_b32 s5, v254, 0
	s_and_b64 vcc, exec, s[4:5]
	s_waitcnt lgkmcnt(0)
	v_pk_fma_f32 v[38:39], v[4:5], v[2:3], v[36:37] op_sel_hi:[1,0,1] neg_lo:[0,0,1] neg_hi:[0,0,1]
	ds_read2st64_b32 v[4:5], v84 offset0:18 offset1:19
	s_waitcnt lgkmcnt(0)
	v_pk_fma_f32 v[40:41], v[6:7], v[2:3], v[4:5] op_sel_hi:[1,0,1] neg_lo:[0,0,1] neg_hi:[0,0,1]
	ds_read2st64_b32 v[4:5], v84 offset0:20 offset1:21
	s_waitcnt lgkmcnt(0)
	v_pk_fma_f32 v[36:37], v[8:9], v[2:3], v[4:5] op_sel_hi:[1,0,1] neg_lo:[0,0,1] neg_hi:[0,0,1]
	ds_read2st64_b32 v[4:5], v84 offset0:22 offset1:23
	s_waitcnt lgkmcnt(0)
	v_pk_fma_f32 v[42:43], v[10:11], v[2:3], v[4:5] op_sel_hi:[1,0,1] neg_lo:[0,0,1] neg_hi:[0,0,1]
	ds_read2st64_b32 v[4:5], v84 offset0:24 offset1:25
	s_waitcnt lgkmcnt(0)
	v_pk_fma_f32 v[48:49], v[12:13], v[2:3], v[4:5] op_sel_hi:[1,0,1] neg_lo:[0,0,1] neg_hi:[0,0,1]
	ds_read2st64_b32 v[4:5], v84 offset0:26 offset1:27
	s_waitcnt lgkmcnt(0)
	v_pk_fma_f32 v[50:51], v[14:15], v[2:3], v[4:5] op_sel_hi:[1,0,1] neg_lo:[0,0,1] neg_hi:[0,0,1]
	ds_read2st64_b32 v[4:5], v84 offset0:28 offset1:29
	s_waitcnt lgkmcnt(0)
	v_pk_fma_f32 v[44:45], v[16:17], v[2:3], v[4:5] op_sel_hi:[1,0,1] neg_lo:[0,0,1] neg_hi:[0,0,1]
	ds_read_b32 v4, v84 offset:7680
	s_waitcnt lgkmcnt(0)
	v_fma_f32 v52, v18, v2, -v4
	s_cbranch_vccnz .LBB0_624
	v_mov_b64_e32 v[4:5], v[20:21]
	v_mov_b64_e32 v[156:157], v[158:159]
	v_mov_b64_e32 v[6:7], v[22:23]
	v_mov_b64_e32 v[8:9], v[24:25]
	v_mov_b64_e32 v[10:11], v[26:27]
	v_mov_b64_e32 v[12:13], v[28:29]
	v_mov_b64_e32 v[14:15], v[30:31]
	v_mov_b64_e32 v[16:17], v[32:33]
	v_mov_b64_e32 v[18:19], v[34:35]
	s_branch .LBB0_625
.LBB0_703:
	v_readlane_b32 s0, v255, 13
	v_readlane_b32 s4, v252, 7
	s_add_i32 s10, s0, 4
	v_readlane_b32 s7, v252, 10
	s_cmp_lt_i32 s10, s7
	v_readlane_b32 s5, v252, 8
	v_readlane_b32 s6, v252, 9
	s_cbranch_scc0 .LBB0_757
	s_waitcnt vmcnt(0)
	s_barrier
	s_mov_b64 s[0:1], exec
	v_readlane_b32 s4, v252, 11
	v_readlane_b32 s5, v252, 12
	s_and_b64 s[4:5], s[0:1], s[4:5]
	s_mov_b64 exec, s[4:5]
	s_cbranch_execz .LBB0_756
	v_readlane_b32 s4, v254, 61
	s_waitcnt vmcnt(0) expcnt(0) lgkmcnt(0)
	s_nop 0
	v_mov_b32_e32 v1, s4
	ds_read_b32 v4, v1
	v_readlane_b32 s4, v254, 62
	s_waitcnt lgkmcnt(0)
	v_cmp_ne_u32_e32 vcc, 0, v4
	v_mov_b32_e32 v1, s4
	ds_read_b32 v2, v1
	s_cbranch_vccnz .LBB0_720
	v_readlane_b32 s6, v252, 2
	v_readlane_b32 s7, v252, 3
	s_load_dwordx2 s[4:5], s[6:7], 0x4
	v_readlane_b32 s6, v252, 4
	s_mov_b32 s14, 1
	s_waitcnt lgkmcnt(0)
	s_mul_i32 s11, s4, s6
	s_mul_i32 s11, s11, s5
	s_branch .LBB0_708
